# DA: conflict-free V layout, 3 V buffers, staggered wave halves (deferred PV), parallel bias lookup; FFN epilogue row-stat prefetch; prep descriptor search resume
# speedup vs baseline: 1.0498x; 1.0139x over previous
; __device__ __forceinline__ void prep_phase(const Params& p, KArgsP kap, char* shm, int wv) {
;     ...
;   float* tl = (float*)shm;
;   for (int t = bid; t < kap->total_wtiles; t += G) {
;     int wi = 0;
;     while (wi + 1 < kap->nwd && kap->wd[wi + 1].tile0 <= t) ++wi;
;     const float* src = kap->wd[wi].src; u16* dst = kap->wd[wi].dst; const float* gain = kap->wd[wi].gain;
;     int K = kap->wd[wi].K, N = kap->wd[wi].N, perm = kap->wd[wi].perm;
;     int lt = t - kap->wd[wi].tile0, nNt = N >> 6;
;     int k0 = (lt / nNt) * 64, n0 = (lt % nNt) * 64;
.LBB0_24:
	s_load_dword s4, s[2:3], 0x4e8
	v_ashrrev_i32_e32 v16, 3, v2
	s_movk_i32 s5, 0x104
	v_lshlrev_b32_e32 v2, 3, v2
	v_mul_lo_u32 v3, v16, s5
	v_and_b32_e32 v2, 56, v2
	v_add_u32_e32 v3, 0, v3
	v_lshlrev_b32_e32 v4, 8, v16
	s_waitcnt lgkmcnt(0)
	s_max_i32 s4, s4, 1
	v_lshl_add_u32 v17, v2, 2, v3
	v_sub_u32_e32 v3, v3, v4
	s_add_i32 s12, s4, -1
	v_mul_u32_u24_e32 v4, 0x104, v2
	v_mov_b32_e32 v11, 0
	s_add_u32 s14, s2, 0xd4
	v_add_u32_e32 v18, v3, v4
	s_mov_b32 s13, 0
	s_addc_u32 s15, s3, 0
	s_add_u32 s21, s4, -1
	v_lshlrev_b32_e32 v10, 2, v2
	s_mov_b32 s22, 0x2e8ba2e9
	s_movk_i32 s23, 0x7f
	v_lshlrev_b32_e32 v12, 1, v2
	v_add_u32_e32 v19, 0x400, v18
	v_mov_b32_e32 v13, v11
	s_mov_b32 s24, s72
	s_mov_b32 s28, 0
	s_branch .LBB0_26

; __device__ __forceinline__ void prep_phase(const Params& p, KArgsP kap, char* shm, int wv) {
;     ...
;     int wi = 0;
;     while (wi + 1 < kap->nwd && kap->wd[wi + 1].tile0 <= t) ++wi;
.LBB0_26:
	s_mul_i32 s4, s28, 40
	s_add_u32 s4, s14, s4
	s_addc_u32 s5, s15, 0
	s_mov_b32 s6, s28
	s_mov_b32 s7, 0
	s_branch .LBB0_28

; __device__ __forceinline__ void prep_phase(const Params& p, KArgsP kap, char* shm, int wv) {
;     ...
;     while (wi + 1 < kap->nwd && kap->wd[wi + 1].tile0 <= t) ++wi;
;     const float* src = kap->wd[wi].src; u16* dst = kap->wd[wi].dst; const float* gain = kap->wd[wi].gain;
;     int K = kap->wd[wi].K, N = kap->wd[wi].N, perm = kap->wd[wi].perm;
;     int lt = t - kap->wd[wi].tile0, nNt = N >> 6;
;     int k0 = (lt / nNt) * 64, n0 = (lt % nNt) * 64;
;     {
;       int kk = tid >> 3, seg = (tid & 7) * 8;
;       const float4* s4 = (const float4*)(src + (long)(k0 + kk) * N + n0 + seg);
;       float4 a = s4[0], b = s4[1]; float g = gain ? gain[k0 + kk] : 1.f;
.LBB0_30:
	s_mov_b32 s28, s16
	s_mul_i32 s4, s17, 40
	s_mul_hi_u32 s5, s16, 40
	s_add_i32 s5, s5, s4
	s_mul_i32 s4, s16, 40
	s_add_u32 s16, s2, s4
	s_addc_u32 s17, s3, s5
	s_load_dwordx4 s[4:7], s[16:17], 0xa0
	s_load_dwordx4 s[8:11], s[16:17], 0x88
	s_waitcnt lgkmcnt(0)
	s_ashr_i32 s18, s5, 6
	s_abs_i32 s19, s18
	v_cvt_f32_u32_e32 v3, s19
	s_sub_i32 s25, 0, s19
	s_sub_i32 s7, s24, s7
	v_mov_b32_e32 v2, s8
	v_rcp_iflag_f32_e32 v4, v3
	v_mov_b32_e32 v3, s9
	s_abs_i32 s9, s7
	s_xor_b32 s8, s7, s18
	v_mul_f32_e32 v4, 0x4f7ffffe, v4
	v_cvt_u32_f32_e32 v4, v4
	s_ashr_i32 s8, s8, 31
	s_load_dwordx2 s[16:17], s[16:17], 0x98
	v_readfirstlane_b32 s26, v4
	s_mul_i32 s25, s25, s26
	s_mul_hi_u32 s25, s26, s25
	s_add_i32 s26, s26, s25
	s_mul_hi_u32 s25, s9, s26
	s_mul_i32 s26, s25, s19
	s_sub_i32 s9, s9, s26
	s_add_i32 s27, s25, 1
	s_sub_i32 s26, s9, s19
	s_cmp_ge_u32 s9, s19
	s_cselect_b32 s25, s27, s25
	s_cselect_b32 s9, s26, s9
	s_add_i32 s26, s25, 1
	s_cmp_ge_u32 s9, s19
	s_cselect_b32 s9, s26, s25
	s_xor_b32 s9, s9, s8
	s_sub_i32 s9, s9, s8
	s_lshl_b32 s8, s9, 6
	s_mul_i32 s9, s9, s18
	s_sub_i32 s7, s7, s9
	v_add_u32_e32 v14, s8, v16
	s_lshl_b32 s18, s7, 6
	v_mad_i64_i32 v[4:5], s[26:27], v14, s5, 0
	v_lshl_add_u64 v[2:3], v[4:5], 2, v[2:3]
	s_ashr_i32 s19, s18, 31
	v_lshl_add_u64 v[2:3], s[18:19], 2, v[2:3]
	v_lshl_add_u64 v[20:21], v[2:3], 0, v[10:11]
	global_load_dwordx4 v[2:5], v[20:21], off offset:16
	global_load_dwordx4 v[6:9], v[20:21], off
	s_waitcnt lgkmcnt(0)
	s_cmp_eq_u64 s[16:17], 0
	s_cbranch_scc1 .LBB0_32
	v_ashrrev_i32_e32 v15, 31, v14
	v_lshl_add_u64 v[14:15], v[14:15], 2, s[16:17]
	global_load_dword v14, v[14:15], off
	s_branch .LBB0_33

; template <int NC, int DQK, int DV, bool CAUSAL, bool PF> ...
;     ...
;     _Pragma("unroll") for (int k2 = 0; k2 < 2; ++k2) _Pragma("unroll") for (int v = 0; v < NVT; ++v) {
;       bf16x8 a = *(const bf16x8*)&Vb[(16 * v + fr) * VLD + 32 * k2 + fq * 8];
;       _Pragma("unroll") for (int c = 0; c < NC; ++c) O[c][v] = __builtin_amdgcn_mfma_f32_16x16x32_bf16(a, pf[c][k2], O[c][v], 0, 0, 0);
;       if ((v & 3) == 3) __builtin_amdgcn_sched_barrier(0);
;     }
.LBB0_1776:
	s_or_b64 exec, exec, s[6:7]
	v_exp_f32_e32 v15, v147
	v_cvt_pk_bf16_f32 v117, v6, v7
	v_exp_f32_e32 v7, v123
	v_add3_u32 v32, s31, v32, v193
	v_add_f32_e32 v31, v15, v146
	v_add_f32_e32 v192, v192, v31
	v_cvt_pk_bf16_f32 v116, v4, v5
	v_add_f32_e32 v4, v7, v122
	v_cvt_pk_bf16_f32 v6, v28, v29
	v_cvt_pk_bf16_f32 v7, v30, v7
	ds_read_b128 v[28:31], v32 offset:39936
	v_cvt_pk_bf16_f32 v114, v0, v1
	v_cvt_pk_bf16_f32 v115, v2, v3
	v_cvt_pk_bf16_f32 v0, v8, v9
	v_cvt_pk_bf16_f32 v1, v10, v11
	v_cvt_pk_bf16_f32 v8, v16, v17
	v_cvt_pk_bf16_f32 v9, v18, v19
	v_cvt_pk_bf16_f32 v10, v20, v21
	v_cvt_pk_bf16_f32 v11, v22, v23
	s_waitcnt lgkmcnt(0)
	v_mfma_f32_16x16x32_bf16 v[90:93], v[28:31], v[114:117], v[90:93]
	v_cvt_pk_bf16_f32 v2, v12, v13
	v_cvt_pk_bf16_f32 v3, v14, v15
	ds_read_b128 v[12:15], v32 offset:34816
	ds_read_b128 v[20:23], v32 offset:37376
	v_mfma_f32_16x16x32_bf16 v[28:31], v[28:31], v[8:11], v[94:97]
	v_add_f32_e32 v191, v191, v4
	v_cvt_pk_bf16_f32 v4, v24, v25
	v_cvt_pk_bf16_f32 v5, v26, v27
	ds_read_b128 v[94:97], v32 offset:42496
	s_waitcnt lgkmcnt(0)
	v_mfma_f32_16x16x32_bf16 v[78:81], v[94:97], v[114:117], v[78:81]
	v_mfma_f32_16x16x32_bf16 v[74:77], v[94:97], v[8:11], v[74:77]
	v_mfma_f32_16x16x32_bf16 v[16:19], v[12:15], v[114:117], v[106:109]
	v_mfma_f32_16x16x32_bf16 v[12:15], v[12:15], v[8:11], v[110:113]
	v_mfma_f32_16x16x32_bf16 v[24:27], v[20:23], v[114:117], v[98:101]
	v_mfma_f32_16x16x32_bf16 v[20:23], v[20:23], v[8:11], v[102:105]
	ds_read_b128 v[94:97], v32 offset:45056
	s_waitcnt lgkmcnt(0)
	v_mfma_f32_16x16x32_bf16 v[62:65], v[94:97], v[114:117], v[62:65]
	v_mfma_f32_16x16x32_bf16 v[70:73], v[94:97], v[8:11], v[70:73]
	ds_read_b128 v[94:97], v32 offset:47616
	s_waitcnt lgkmcnt(0)
	v_mfma_f32_16x16x32_bf16 v[50:53], v[94:97], v[114:117], v[50:53]
	v_mfma_f32_16x16x32_bf16 v[66:69], v[94:97], v[8:11], v[66:69]
	ds_read_b128 v[94:97], v32 offset:50176
	s_waitcnt lgkmcnt(0)
	v_mfma_f32_16x16x32_bf16 v[54:57], v[94:97], v[114:117], v[54:57]
	v_mfma_f32_16x16x32_bf16 v[58:61], v[94:97], v[8:11], v[58:61]
	ds_read_b128 v[94:97], v32 offset:52736
	s_waitcnt lgkmcnt(0)
	v_mfma_f32_16x16x32_bf16 v[82:85], v[94:97], v[114:117], v[82:85]
	v_mfma_f32_16x16x32_bf16 v[8:11], v[94:97], v[8:11], v[86:89]
	s_nop 2
	ds_read_b128 v[86:89], v32 offset:34880
	s_waitcnt lgkmcnt(0)
	v_mfma_f32_16x16x32_bf16 v[110:113], v[86:89], v[4:7], v[12:15]
	s_nop 2
	ds_read_b128 v[12:15], v32 offset:37440
	v_mfma_f32_16x16x32_bf16 v[106:109], v[86:89], v[0:3], v[16:19]
	s_waitcnt lgkmcnt(0)
	v_mfma_f32_16x16x32_bf16 v[98:101], v[12:15], v[0:3], v[24:27]
	v_mfma_f32_16x16x32_bf16 v[102:105], v[12:15], v[4:7], v[20:23]
	ds_read_b128 v[12:15], v32 offset:40000
	s_waitcnt lgkmcnt(0)
	v_mfma_f32_16x16x32_bf16 v[90:93], v[12:15], v[0:3], v[90:93]
	v_mfma_f32_16x16x32_bf16 v[94:97], v[12:15], v[4:7], v[28:31]
	ds_read_b128 v[12:15], v32 offset:42560
	s_waitcnt lgkmcnt(0)
	v_mfma_f32_16x16x32_bf16 v[78:81], v[12:15], v[0:3], v[78:81]
	v_mfma_f32_16x16x32_bf16 v[74:77], v[12:15], v[4:7], v[74:77]
	ds_read_b128 v[12:15], v32 offset:45120
	s_waitcnt lgkmcnt(0)
	v_mfma_f32_16x16x32_bf16 v[62:65], v[12:15], v[0:3], v[62:65]
	v_mfma_f32_16x16x32_bf16 v[70:73], v[12:15], v[4:7], v[70:73]
	ds_read_b128 v[12:15], v32 offset:47680
	s_waitcnt lgkmcnt(0)
	v_mfma_f32_16x16x32_bf16 v[50:53], v[12:15], v[0:3], v[50:53]
	v_mfma_f32_16x16x32_bf16 v[66:69], v[12:15], v[4:7], v[66:69]
	ds_read_b128 v[12:15], v32 offset:50240
	s_waitcnt lgkmcnt(0)
	v_mfma_f32_16x16x32_bf16 v[54:57], v[12:15], v[0:3], v[54:57]
	v_mfma_f32_16x16x32_bf16 v[58:61], v[12:15], v[4:7], v[58:61]
	ds_read_b128 v[12:15], v32 offset:52800
	s_waitcnt lgkmcnt(0)
	v_mfma_f32_16x16x32_bf16 v[82:85], v[12:15], v[0:3], v[82:85]
	v_mfma_f32_16x16x32_bf16 v[86:89], v[12:15], v[4:7], v[8:11]

; __device__ __forceinline__ int opaque_tid(int wv) { unsigned ones = ~0u; asm volatile("" : "+s"(ones)); int lane = __builtin_amdgcn_mbcnt_hi(ones, __builtin_amdgcn_mbcnt_lo(ones, 0u)); int t = (wv << 6) | lane; asm volatile("" : "+v"(t)); return t; }
; template <int NC, int DQK, int DV, bool CAUSAL, bool PF> ...
;     ...
;   int tid = opaque_tid(wv), wid = tid >> 6, lane = tid & 63, fr = lane & 15, fq = lane >> 4;
;   int qw0 = q0 + wid * 16, qpos = qw0 + fr;
;   bf16x8 qf[NC][NKS];
;   _Pragma("unroll") for (int c = 0; c < NC; ++c) _Pragma("unroll") for (int ks = 0; ks < NKS; ++ks)
;     qf[c][ks] = *(const bf16x8*)&Qg[(long)(wid * 16 + fr) * q_stride + c * DQK + ks * 32 + fq * 8];
;   f32x4 O[NC][NVT];
;   _Pragma("unroll") for (int c = 0; c < NC; ++c) _Pragma("unroll") for (int v = 0; v < NVT; ++v) O[c][v] = f32x4{0.f, 0.f, 0.f, 0.f};
;   float mrun[NC], lsum[NC];
;   _Pragma("unroll") for (int c = 0; c < NC; ++c) { mrun[c] = -1e30f; lsum[c] = 0.f; }
;   const __amdgpu_buffer_rsrc_t rsK = __builtin_amdgcn_make_buffer_rsrc((void*)Kg, 0, 0x7fffffff, 0x00020000);
;   const __amdgpu_buffer_rsrc_t rsV = __builtin_amdgcn_make_buffer_rsrc((void*)VTg, 0, 0x7fffffff, 0x00020000);
;   const __amdgpu_buffer_rsrc_t rsNK = __builtin_amdgcn_make_buffer_rsrc((void*)nKg, 0, 0x7fffffff, 0x00020000);
;   const __amdgpu_buffer_rsrc_t rsNV = __builtin_amdgcn_make_buffer_rsrc((void*)nVTg, 0, 0x7fffffff, 0x00020000);
;   int kvo[KPT], vvo[VPT];
;   _Pragma("unroll") for (int i = 0; i < KPT; ++i) { int id = tid + i * 512, row = id / KCH, cc = id % KCH; kvo[i] = (row * k_stride + cc * 8) * 2; }
;   _Pragma("unroll") for (int i = 0; i < VPT; ++i) { int id = tid + i * 512, row = id >> 3, cc = id & 7; vvo[i] = (row * vt_stride + cc * 8) * 2; }
;     ...
;     _Pragma("unroll") for (int k2 = 0; k2 < 2; ++k2) _Pragma("unroll") for (int v = 0; v < NVT; ++v) {
;       bf16x8 a = *(const bf16x8*)&Vb[(16 * v + fr) * VLD + 32 * k2 + fq * 8];
;       _Pragma("unroll") for (int c = 0; c < NC; ++c) O[c][v] = __builtin_amdgcn_mfma_f32_16x16x32_bf16(a, pf[c][k2], O[c][v], 0, 0, 0);
;       if ((v & 3) == 3) __builtin_amdgcn_sched_barrier(0);
;     }
.LBB0_1782:
	s_lshl_b64 s[18:19], s[0:1], 10
	v_and_b32_e32 v6, 63, v0
	v_and_b32_e32 v196, 15, v0
	v_bfe_u32 v7, v0, 4, 2
	v_and_b32_e32 v206, 32, v5
	v_lshlrev_b32_e32 v5, 4, v0
	v_lshlrev_b32_e32 v8, 1, v0
	v_lshrrev_b32_e32 v0, 3, v0
	s_movk_i32 s0, 0xa0
	v_mul_lo_u32 v208, v0, s0
	v_lshrrev_b32_e32 v0, 3, v3
	v_and_b32_e32 v1, -16, v1
	v_mul_lo_u32 v207, v0, s0
	s_sub_i32 s0, s8, 51
	v_mov_b32_e32 v52, v33
	v_mov_b32_e32 v53, v33
	s_lshr_b32 s30, s8, 6
	v_add_u32_e32 v197, s8, v1
	v_and_b32_e32 v5, 16, v5
	v_and_b32_e32 v8, 4, v8
	v_lshlrev_b32_e32 v6, 2, v6
	v_lshlrev_b32_e32 v190, 2, v7
	v_add3_u32 v0, s0, v1, v196
	v_mov_b32_e32 v50, v33
	v_mov_b32_e32 v51, v33
	v_mov_b64_e32 v[64:65], v[52:53]
	v_mov_b64_e32 v[80:81], v[52:53]
	v_mov_b64_e32 v[92:93], v[52:53]
	v_mov_b64_e32 v[100:101], v[52:53]
	v_mov_b64_e32 v[108:109], v[52:53]
	v_mov_b64_e32 v[56:57], v[52:53]
	v_mov_b64_e32 v[84:85], v[52:53]
	v_mov_b64_e32 v[112:113], v[52:53]
	v_mov_b64_e32 v[104:105], v[52:53]
	v_mov_b64_e32 v[96:97], v[52:53]
	v_mov_b64_e32 v[76:77], v[52:53]
	v_mov_b64_e32 v[72:73], v[52:53]
	v_mov_b64_e32 v[68:69], v[52:53]
	v_mov_b64_e32 v[60:61], v[52:53]
	v_mov_b64_e32 v[88:89], v[52:53]
	v_or_b32_e32 v203, 15, v197
	v_add_u32_e32 v202, 0xffffff8f, v197
	s_movk_i32 s31, 0x80
	v_xor_b32_e32 v189, 0x80, v6
	v_mul_lo_u32 v210, v2, s74
	v_mul_lo_u32 v209, v4, s74
	v_mul_u32_u24_e32 v195, 0x110, v196
	v_mul_u32_u24_e32 v193, 0xa0, v196
	s_add_i32 s30, s30, 1
	v_sub_u32_e32 v213, v0, v190
	s_mov_b32 s34, 0
	v_mov_b32_e32 v191, 0
	v_mov_b32_e32 v171, 0xf149f2ca
	s_mov_b32 s35, 63
	s_mov_b32 s36, 0x20000
	v_lshlrev_b32_e32 v211, 1, v5
	v_lshlrev_b32_e32 v212, 1, v8
	v_mov_b64_e32 v[62:63], v[50:51]
	v_mov_b64_e32 v[78:79], v[50:51]
	v_mov_b64_e32 v[90:91], v[50:51]
	v_mov_b64_e32 v[98:99], v[50:51]
	v_mov_b64_e32 v[106:107], v[50:51]
	v_mov_b32_e32 v194, 0xf149f2ca
	v_mov_b32_e32 v192, 0
	v_mov_b64_e32 v[54:55], v[50:51]
	v_mov_b64_e32 v[82:83], v[50:51]
	v_mov_b64_e32 v[110:111], v[50:51]
	v_mov_b64_e32 v[102:103], v[50:51]
	v_mov_b64_e32 v[94:95], v[50:51]
	v_mov_b64_e32 v[74:75], v[50:51]
	v_mov_b64_e32 v[70:71], v[50:51]
	v_mov_b64_e32 v[66:67], v[50:51]
	v_mov_b64_e32 v[58:59], v[50:51]
	v_mov_b64_e32 v[86:87], v[50:51]
	s_branch .LBB0_1785
.LBB0_1783:
	s_or_b64 exec, exec, s[6:7]
	v_exp_f32_e32 v15, v173
	v_cvt_pk_bf16_f32 v149, v6, v7
	v_exp_f32_e32 v7, v175
	v_add3_u32 v150, s37, v32, v193
	v_add_f32_e32 v31, v15, v172
	v_add_f32_e32 v192, v192, v31
	v_cvt_pk_bf16_f32 v148, v4, v5
	v_add_f32_e32 v4, v7, v174
	v_cvt_pk_bf16_f32 v6, v28, v29
	v_cvt_pk_bf16_f32 v7, v30, v7
	ds_read_b128 v[28:31], v150 offset:39936
	v_cvt_pk_bf16_f32 v146, v0, v1
	v_cvt_pk_bf16_f32 v147, v2, v3
	v_cvt_pk_bf16_f32 v0, v8, v9
	v_cvt_pk_bf16_f32 v1, v10, v11
	v_cvt_pk_bf16_f32 v8, v16, v17
	v_cvt_pk_bf16_f32 v9, v18, v19
	v_cvt_pk_bf16_f32 v10, v20, v21
	v_cvt_pk_bf16_f32 v11, v22, v23
	s_waitcnt lgkmcnt(0)
	v_mfma_f32_16x16x32_bf16 v[90:93], v[28:31], v[146:149], v[90:93]
	v_cvt_pk_bf16_f32 v2, v12, v13
	v_cvt_pk_bf16_f32 v3, v14, v15
	ds_read_b128 v[12:15], v150 offset:34816
	ds_read_b128 v[20:23], v150 offset:37376
	v_mfma_f32_16x16x32_bf16 v[28:31], v[28:31], v[8:11], v[94:97]
	v_add_f32_e32 v191, v191, v4
	v_cvt_pk_bf16_f32 v4, v24, v25
	v_cvt_pk_bf16_f32 v5, v26, v27
	ds_read_b128 v[94:97], v150 offset:42496
	s_waitcnt lgkmcnt(0)
	v_mfma_f32_16x16x32_bf16 v[78:81], v[94:97], v[146:149], v[78:81]
	v_mfma_f32_16x16x32_bf16 v[74:77], v[94:97], v[8:11], v[74:77]
	v_mfma_f32_16x16x32_bf16 v[16:19], v[12:15], v[146:149], v[106:109]
	v_mfma_f32_16x16x32_bf16 v[12:15], v[12:15], v[8:11], v[110:113]
	v_mfma_f32_16x16x32_bf16 v[24:27], v[20:23], v[146:149], v[98:101]
	v_mfma_f32_16x16x32_bf16 v[20:23], v[20:23], v[8:11], v[102:105]
	ds_read_b128 v[94:97], v150 offset:45056
	s_waitcnt lgkmcnt(0)
	v_mfma_f32_16x16x32_bf16 v[62:65], v[94:97], v[146:149], v[62:65]
	v_mfma_f32_16x16x32_bf16 v[70:73], v[94:97], v[8:11], v[70:73]
	ds_read_b128 v[94:97], v150 offset:47616
	s_waitcnt lgkmcnt(0)
	v_mfma_f32_16x16x32_bf16 v[50:53], v[94:97], v[146:149], v[50:53]
	v_mfma_f32_16x16x32_bf16 v[66:69], v[94:97], v[8:11], v[66:69]
	ds_read_b128 v[94:97], v150 offset:50176
	s_waitcnt lgkmcnt(0)
	v_mfma_f32_16x16x32_bf16 v[54:57], v[94:97], v[146:149], v[54:57]
	v_mfma_f32_16x16x32_bf16 v[58:61], v[94:97], v[8:11], v[58:61]
	ds_read_b128 v[94:97], v150 offset:52736
	s_waitcnt lgkmcnt(0)
	v_mfma_f32_16x16x32_bf16 v[82:85], v[94:97], v[146:149], v[82:85]
	v_mfma_f32_16x16x32_bf16 v[8:11], v[94:97], v[8:11], v[86:89]
	s_nop 2
	ds_read_b128 v[86:89], v150 offset:34880
	s_waitcnt lgkmcnt(0)
	v_mfma_f32_16x16x32_bf16 v[110:113], v[86:89], v[4:7], v[12:15]
	s_nop 2
	ds_read_b128 v[12:15], v150 offset:37440
	v_mfma_f32_16x16x32_bf16 v[106:109], v[86:89], v[0:3], v[16:19]
	s_waitcnt lgkmcnt(0)
	v_mfma_f32_16x16x32_bf16 v[98:101], v[12:15], v[0:3], v[24:27]
	v_mfma_f32_16x16x32_bf16 v[102:105], v[12:15], v[4:7], v[20:23]
	ds_read_b128 v[12:15], v150 offset:40000
	s_waitcnt lgkmcnt(0)
	v_mfma_f32_16x16x32_bf16 v[90:93], v[12:15], v[0:3], v[90:93]
	v_mfma_f32_16x16x32_bf16 v[94:97], v[12:15], v[4:7], v[28:31]
	ds_read_b128 v[12:15], v150 offset:42560
	s_waitcnt lgkmcnt(0)
	v_mfma_f32_16x16x32_bf16 v[78:81], v[12:15], v[0:3], v[78:81]
	v_mfma_f32_16x16x32_bf16 v[74:77], v[12:15], v[4:7], v[74:77]
	ds_read_b128 v[12:15], v150 offset:45120
	s_waitcnt lgkmcnt(0)
	v_mfma_f32_16x16x32_bf16 v[62:65], v[12:15], v[0:3], v[62:65]
	v_mfma_f32_16x16x32_bf16 v[70:73], v[12:15], v[4:7], v[70:73]
	ds_read_b128 v[12:15], v150 offset:47680
	s_waitcnt lgkmcnt(0)
	v_mfma_f32_16x16x32_bf16 v[50:53], v[12:15], v[0:3], v[50:53]
	v_mfma_f32_16x16x32_bf16 v[66:69], v[12:15], v[4:7], v[66:69]
	ds_read_b128 v[12:15], v150 offset:50240
	s_waitcnt lgkmcnt(0)
	v_mfma_f32_16x16x32_bf16 v[54:57], v[12:15], v[0:3], v[54:57]
	v_mfma_f32_16x16x32_bf16 v[58:61], v[12:15], v[4:7], v[58:61]
	ds_read_b128 v[12:15], v150 offset:52800
	s_waitcnt lgkmcnt(0)
	v_mfma_f32_16x16x32_bf16 v[82:85], v[12:15], v[0:3], v[82:85]
	v_mfma_f32_16x16x32_bf16 v[86:89], v[12:15], v[4:7], v[8:11]

; #define FA_PREFETCH(kt_) do { int k0_ = (kt_) * 64; \
;     _Pragma("unroll") for (int i = 0; i < KPT; ++i) kreg[i] = __builtin_amdgcn_raw_buffer_load_b128(rsK, kvo[i], k0_ * k_stride * 2, 0); \
;     _Pragma("unroll") for (int i = 0; i < VPT; ++i) vreg[i] = __builtin_amdgcn_raw_buffer_load_b128(rsV, vvo[i], k0_ * 2, 0); } while (0)
; template <int NC, int DQK, int DV, bool CAUSAL, bool PF> ...
;     ...
;   for (int kt = 0; kt < nkt; ++kt) {
;     if (!PF) FA_PREFETCH(kt);
;     u16* Kb = Ks + (kt & 1) * KBUF; u16* Vb = Vs + (kt & 1) * VBUF;
;     _Pragma("unroll") for (int i = 0; i < KPT; ++i) { int id = tid + i * 512, row = id / KCH, cc = id % KCH; *(u32x4*)&Kb[row * KLD + cc * 8] = kreg[i]; }
;     _Pragma("unroll") for (int i = 0; i < VPT; ++i) {
;       int id = tid + i * 512, row = id >> 3, cc = id & 7;
;       int pos = 32 * (cc >> 2) + 16 * (cc & 1) + 4 * ((cc >> 1) & 1);
;       uint2 lo2, hi2; lo2.x = vreg[i][0]; lo2.y = vreg[i][1]; hi2.x = vreg[i][2]; hi2.y = vreg[i][3];
;       *(uint2*)&Vb[row * VLD + pos] = lo2; *(uint2*)&Vb[row * VLD + pos + 8] = hi2;
;     }
;     __syncthreads();
;     if (PF && kt + 1 < nkt) FA_PREFETCH(kt + 1); else if (PF && has_next_item) FA_PREFETCH_NEXT();
;     int k0 = kt * 64;
;     if (CAUSAL && k0 > qw0 + 15) continue;
;     bf16x8 pf[NC][2];
;     bool general = false; float bb = 0.f;
;     if (CAUSAL) { general = (qw0 - (k0 + 63)) < 113; bb = btab[127]; }
;     f32x4 bv[4];
;     if (general) {
;       bool diag = (k0 + 63) > qw0;
;       _Pragma("unroll") for (int m = 0; m < 4; ++m) _Pragma("unroll") for (int j = 0; j < 4; ++j) {
;         int dist = qpos - (k0 + 16 * m + fq * 4 + j);
;         int di = dist < 0 ? 0 : (dist > 127 ? 127 : dist);
;         float b = btab[di];
;         bv[m][j] = (diag && dist < 0) ? -1e30f : b;
;       }
;     }
;     _Pragma("unroll") for (int c = 0; c < NC; ++c) {
;       f32x4 s[4];
;       _Pragma("unroll") for (int m = 0; m < 4; ++m) s[m] = f32x4{0.f, 0.f, 0.f, 0.f};
;       _Pragma("unroll") for (int ks = 0; ks < NKS; ++ks) _Pragma("unroll") for (int m = 0; m < 4; ++m) {
;         bf16x8 a = *(const bf16x8*)&Kb[(16 * m + fr) * KLD + c * DQK + ks * 32 + fq * 8];
;         s[m] = __builtin_amdgcn_mfma_f32_16x16x32_bf16(a, qf[c][ks], s[m], 0, 0, 0);
.LBB0_1785:
	s_and_b32 s0, s34, 1
	s_mul_i32 s1, s0, 0x4400
	s_add_i32 s38, s1, 0
	v_add3_u32 v0, s38, v210, v204
	s_mul_hi_u32 s0, s34, 0xaaaaaaab
	s_lshr_b32 s0, s0, 1
	s_mul_i32 s0, s0, 3
	s_sub_i32 s0, s34, s0
	s_mul_i32 s0, s0, 0x5000
	s_waitcnt vmcnt(3)
	ds_write_b128 v0, v[34:37]
	v_add3_u32 v0, s38, v209, v205
	s_mov_b32 s37, s0
	s_waitcnt vmcnt(2)
	ds_write_b128 v0, v[38:41]
	v_lshl_add_u32 v0, v206, 1, s37
	v_add3_u32 v0, v0, v211, v212
	v_add_u32_e32 v1, v0, v208
	v_add_u32_e32 v0, v0, v207
	v_add_u32_e32 v1, 0x8800, v1
	v_add_u32_e32 v0, 0x8800, v0
	s_mov_b32 s14, s78
	s_mov_b32 s15, s79
	s_waitcnt vmcnt(0)
	ds_write2_b64 v1, v[42:43], v[44:45] offset1:2
	s_waitcnt vmcnt(0)
	ds_write2_b64 v0, v[46:47], v[48:49] offset1:2
	s_waitcnt lgkmcnt(0)
	s_barrier
	buffer_load_dwordx4 v[34:37], v198, s[76:79], s36 offen
	buffer_load_dwordx4 v[38:41], v199, s[76:79], s36 offen
	buffer_load_dwordx4 v[46:49], v200, s[12:15], s31 offen
	buffer_load_dwordx4 v[42:45], v201, s[12:15], s31 offen
	s_sub_i32 s0, s35, 63
	v_cmp_le_i32_e32 vcc, s0, v203
	s_and_saveexec_b64 s[0:1], vcc
	s_cbranch_execz .LBB0_1784
	v_readlane_b32 s6, v254, 39
	v_cmp_gt_i32_e32 vcc, s35, v202
	s_nop 0
	v_mov_b32_e32 v0, s6
	ds_read_b32 v170, v0
	v_cmp_le_i32_e64 s[6:7], s35, v202
	s_cbranch_vccz .Lda_fast_sel
	s_cmp_lt_u32 s97, 0x100
	s_cbranch_scc1 .Lda_gen_cont
	s_cmp_eq_u32 s34, 0
	s_cbranch_scc1 .Lda_gen_cont
	s_sub_i32 s8, s35, 64
	v_cmp_le_i32_e32 vcc, s8, v202
	s_cbranch_vccnz .Ldb_flushB
	v_cmp_gt_i32_e32 vcc, s35, v202
.Lda_gen_cont:
	s_and_saveexec_b64 s[14:15], vcc
	s_cbranch_execz .LBB0_1788
	v_add_u32_e32 v0, 51, v213
	v_add_u32_e32 v1, 50, v213
	v_add_u32_e32 v2, 49, v213
	v_add_u32_e32 v3, 48, v213
	v_add_u32_e32 v4, 35, v213
	v_add_u32_e32 v5, 34, v213
	v_add_u32_e32 v6, 33, v213
	v_add_u32_e32 v7, 32, v213
	v_add_u32_e32 v8, 19, v213
	v_add_u32_e32 v9, 18, v213
	v_add_u32_e32 v10, 17, v213
	v_add_u32_e32 v11, 16, v213
	v_add_u32_e32 v12, 3, v213
	v_add_u32_e32 v13, 2, v213
	v_add_u32_e32 v14, 1, v213
	v_mov_b32_e32 v15, v213
	v_med3_i32 v16, v0, 0, v184
	v_med3_i32 v17, v1, 0, v184
	v_med3_i32 v18, v2, 0, v184
	v_med3_i32 v19, v3, 0, v184
	v_med3_i32 v20, v4, 0, v184
	v_med3_i32 v21, v5, 0, v184
	v_med3_i32 v22, v6, 0, v184
	v_med3_i32 v23, v7, 0, v184
	v_med3_i32 v24, v8, 0, v184
	v_med3_i32 v25, v9, 0, v184
	v_med3_i32 v26, v10, 0, v184
	v_med3_i32 v27, v11, 0, v184
	v_med3_i32 v28, v12, 0, v184
	v_med3_i32 v29, v13, 0, v184
	v_med3_i32 v30, v14, 0, v184
	v_med3_i32 v31, v15, 0, v184
	v_lshl_add_u32 v16, v16, 2, s91
	v_lshl_add_u32 v17, v17, 2, s91
	v_lshl_add_u32 v18, v18, 2, s91
	v_lshl_add_u32 v19, v19, 2, s91
	v_lshl_add_u32 v20, v20, 2, s91
	v_lshl_add_u32 v21, v21, 2, s91
	v_lshl_add_u32 v22, v22, 2, s91
	v_lshl_add_u32 v23, v23, 2, s91
	v_lshl_add_u32 v24, v24, 2, s91
	v_lshl_add_u32 v25, v25, 2, s91
	v_lshl_add_u32 v26, v26, 2, s91
	v_lshl_add_u32 v27, v27, 2, s91
	v_lshl_add_u32 v28, v28, 2, s91
	v_lshl_add_u32 v29, v29, 2, s91
	v_lshl_add_u32 v30, v30, 2, s91
	v_lshl_add_u32 v31, v31, 2, s91
	ds_read_b32 v122, v16
	ds_read_b32 v123, v17
	ds_read_b32 v124, v18
	ds_read_b32 v125, v19
	ds_read_b32 v126, v20
	ds_read_b32 v127, v21
	ds_read_b32 v128, v22
	ds_read_b32 v129, v23
	s_waitcnt lgkmcnt(6)
	ds_read_b32 v130, v24
	ds_read_b32 v131, v25
	ds_read_b32 v132, v26
	ds_read_b32 v133, v27
	ds_read_b32 v142, v28
	ds_read_b32 v143, v29
	ds_read_b32 v144, v30
	ds_read_b32 v145, v31
	v_cmp_gt_i32_e32 vcc, s35, v197
	s_waitcnt lgkmcnt(0)
	s_cbranch_vccz .Ldg_nomask
	v_cmp_gt_i32_e32 vcc, 0, v0
	v_cmp_gt_i32_e64 s[8:9], 0, v1
	s_nop 0
	v_cndmask_b32_e32 v122, v122, v185, vcc
	v_cmp_gt_i32_e32 vcc, 0, v2
	v_cndmask_b32_e64 v123, v123, v185, s[8:9]
	v_cmp_gt_i32_e64 s[8:9], 0, v3
	v_cndmask_b32_e32 v124, v124, v185, vcc
	v_cmp_gt_i32_e32 vcc, 0, v4
	v_cndmask_b32_e64 v125, v125, v185, s[8:9]
	v_cmp_gt_i32_e64 s[8:9], 0, v5
	v_cndmask_b32_e32 v126, v126, v185, vcc
	v_cmp_gt_i32_e32 vcc, 0, v6
	v_cndmask_b32_e64 v127, v127, v185, s[8:9]
	v_cmp_gt_i32_e64 s[8:9], 0, v7
	v_cndmask_b32_e32 v128, v128, v185, vcc
	v_cmp_gt_i32_e32 vcc, 0, v8
	v_cndmask_b32_e64 v129, v129, v185, s[8:9]
	v_cmp_gt_i32_e64 s[8:9], 0, v9
	v_cndmask_b32_e32 v130, v130, v185, vcc
	v_cmp_gt_i32_e32 vcc, 0, v10
	v_cndmask_b32_e64 v131, v131, v185, s[8:9]
	v_cmp_gt_i32_e64 s[8:9], 0, v11
	v_cndmask_b32_e32 v132, v132, v185, vcc
	v_cmp_gt_i32_e32 vcc, 0, v12
	v_cndmask_b32_e64 v133, v133, v185, s[8:9]
	v_cmp_gt_i32_e64 s[8:9], 0, v13
	v_cndmask_b32_e32 v142, v142, v185, vcc
	v_cmp_gt_i32_e32 vcc, 0, v14
	v_cndmask_b32_e64 v143, v143, v185, s[8:9]
	v_cmp_gt_i32_e64 s[8:9], 0, v15
	v_cndmask_b32_e32 v144, v144, v185, vcc
	s_nop 0
	v_cndmask_b32_e64 v145, v145, v185, s[8:9]
.Ldg_nomask:
.LBB0_1788:
	s_or_b64 exec, exec, s[14:15]
	v_add_u32_e32 v0, s38, v32
	v_add_u32_e32 v146, v0, v195
	ds_read_b128 v[0:3], v146
	ds_read_b128 v[16:19], v146 offset:64
	ds_read_b128 v[4:7], v146 offset:4352
	ds_read_b128 v[8:11], v146 offset:8704
	ds_read_b128 v[12:15], v146 offset:13056
	s_waitcnt lgkmcnt(4)
	v_mfma_f32_16x16x32_bf16 v[0:3], v[0:3], v[138:141], 0
	s_waitcnt lgkmcnt(3)
	v_mfma_f32_16x16x32_bf16 v[28:31], v[16:19], v[134:137], v[0:3]
	s_nop 5
	ds_read_b128 v[0:3], v146 offset:4416
	s_waitcnt lgkmcnt(3)
	v_mfma_f32_16x16x32_bf16 v[4:7], v[4:7], v[138:141], 0
	s_waitcnt lgkmcnt(0)
	v_mfma_f32_16x16x32_bf16 v[24:27], v[0:3], v[134:137], v[4:7]
	ds_read_b128 v[0:3], v146 offset:8768
	v_mfma_f32_16x16x32_bf16 v[8:11], v[8:11], v[138:141], 0
	s_waitcnt lgkmcnt(0)
	v_mfma_f32_16x16x32_bf16 v[20:23], v[0:3], v[134:137], v[8:11]
	ds_read_b128 v[0:3], v146 offset:13120
	v_mfma_f32_16x16x32_bf16 v[12:15], v[12:15], v[138:141], 0
	s_waitcnt lgkmcnt(0)
	v_mfma_f32_16x16x32_bf16 v[16:19], v[0:3], v[134:137], v[12:15]
	s_and_saveexec_b64 s[8:9], s[6:7]
	s_xor_b64 s[8:9], exec, s[8:9]
	s_cbranch_execnz .LBB0_1804
	s_andn2_saveexec_b64 s[8:9], s[8:9]
	s_cbranch_execnz .LBB0_1805

; template <int NC, int DQK, int DV, bool CAUSAL, bool PF> ...
;     ...
;     _Pragma("unroll") for (int c = 0; c < NC; ++c) {
;       f32x4 s[4];
;       _Pragma("unroll") for (int m = 0; m < 4; ++m) s[m] = f32x4{0.f, 0.f, 0.f, 0.f};
;       _Pragma("unroll") for (int ks = 0; ks < NKS; ++ks) _Pragma("unroll") for (int m = 0; m < 4; ++m) {
;         bf16x8 a = *(const bf16x8*)&Kb[(16 * m + fr) * KLD + c * DQK + ks * 32 + fq * 8];
;         s[m] = __builtin_amdgcn_mfma_f32_16x16x32_bf16(a, qf[c][ks], s[m], 0, 0, 0);
;       }
;       constexpr float THR = 8.f;
;       float tnew, psum = 0.f;
;       if (general) {
;         float tmax = -1e30f;
;         _Pragma("unroll") for (int m = 0; m < 4; ++m) _Pragma("unroll") for (int j = 0; j < 4; ++j) {
;           float v = s[m][j] * scale_log2 + bv[m][j];
;           s[m][j] = v; tmax = fmaxf(tmax, v);
;         }
;         tnew = tmax;
;       } else {
;         float rmax = fmaxf(fmaxf(s[0][0], s[0][1]), fmaxf(s[0][2], s[0][3]));
;         _Pragma("unroll") for (int m = 1; m < 4; ++m) rmax = fmaxf(rmax, fmaxf(fmaxf(s[m][0], s[m][1]), fmaxf(s[m][2], s[m][3])));
;         tnew = rmax * scale_log2 + bb;
;       }
;       if (__builtin_amdgcn_ballot_w64(tnew - mrun[c] > THR) != 0ull) {
;         tnew = fmaxf(tnew, sx<16>(tnew, lane)); tnew = fmaxf(tnew, sx<32>(tnew, lane));
;         float mnew = fmaxf(mrun[c], tnew);
;         float alpha = __builtin_amdgcn_exp2f(mrun[c] - mnew);
;         mrun[c] = mnew; lsum[c] *= alpha;
;         _Pragma("unroll") for (int v = 0; v < NVT; ++v) _Pragma("unroll") for (int j = 0; j < 4; ++j) O[c][v][j] *= alpha;
;       }
;       if (general) {
;         float mm = mrun[c];
;         _Pragma("unroll") for (int m = 0; m < 4; ++m) _Pragma("unroll") for (int j = 0; j < 4; ++j) { float pv = __builtin_amdgcn_exp2f(s[m][j] - mm); s[m][j] = pv; psum += pv; }
;       } else {
;         float cc = bb - mrun[c];
;         _Pragma("unroll") for (int m = 0; m < 4; ++m) _Pragma("unroll") for (int j = 0; j < 4; ++j) { float pv = __builtin_amdgcn_exp2f(s[m][j] * scale_log2 + cc); s[m][j] = pv; psum += pv; }
;       }
;       lsum[c] += psum;
.Lda_fast_sel:
	s_cmp_lt_u32 s97, 0x100
	s_cbranch_scc0 .Ldb_fastB
.Lda_fast:
	v_add3_u32 v172, s38, v32, v195
	v_add3_u32 v173, s37, v32, v193
	ds_read_b128 v[146:149], v172
	ds_read_b128 v[150:153], v172 offset:4352
	ds_read_b128 v[154:157], v172 offset:8704
	ds_read_b128 v[158:161], v172 offset:13056
	ds_read_b128 v[16:19], v172 offset:64
	ds_read_b128 v[20:23], v172 offset:4416
	ds_read_b128 v[24:27], v172 offset:8768
	ds_read_b128 v[28:31], v172 offset:13120
	ds_read_b128 v[0:3], v172 offset:128
	ds_read_b128 v[4:7], v172 offset:4480
	ds_read_b128 v[8:11], v172 offset:8832
	ds_read_b128 v[12:15], v172 offset:13184
	s_waitcnt lgkmcnt(10)
	v_mfma_f32_16x16x32_bf16 v[146:149], v[146:149], v[138:141], 0
	v_mfma_f32_16x16x32_bf16 v[150:153], v[150:153], v[138:141], 0
	s_waitcnt lgkmcnt(8)
	v_mfma_f32_16x16x32_bf16 v[154:157], v[154:157], v[138:141], 0
	v_mfma_f32_16x16x32_bf16 v[158:161], v[158:161], v[138:141], 0
	s_waitcnt lgkmcnt(4)
	v_mfma_f32_16x16x32_bf16 v[146:149], v[16:19], v[134:137], v[146:149]
	v_mfma_f32_16x16x32_bf16 v[150:153], v[20:23], v[134:137], v[150:153]
	v_mfma_f32_16x16x32_bf16 v[154:157], v[24:27], v[134:137], v[154:157]
	v_mfma_f32_16x16x32_bf16 v[158:161], v[28:31], v[134:137], v[158:161]
	ds_read_b128 v[16:19], v172 offset:192
	ds_read_b128 v[20:23], v172 offset:4544
	ds_read_b128 v[24:27], v172 offset:8896
	ds_read_b128 v[28:31], v172 offset:13248
	ds_read_b128 v[122:125], v173 offset:34816
	ds_read_b128 v[126:129], v173 offset:37376
	ds_read_b128 v[130:133], v173 offset:39936
	ds_read_b128 v[142:145], v173 offset:42496
	s_waitcnt lgkmcnt(8)
	v_mfma_f32_16x16x32_bf16 v[0:3], v[0:3], v[118:121], 0
	v_mfma_f32_16x16x32_bf16 v[4:7], v[4:7], v[118:121], 0
	v_mfma_f32_16x16x32_bf16 v[8:11], v[8:11], v[118:121], 0
	v_mfma_f32_16x16x32_bf16 v[12:15], v[12:15], v[118:121], 0
	v_max3_f32 v174, v146, v147, v148
	v_max3_f32 v175, v149, v150, v151
	v_max3_f32 v174, v174, v152, v153
	v_max3_f32 v175, v175, v154, v155
	v_max3_f32 v174, v174, v156, v157
	v_max3_f32 v175, v175, v158, v159
	v_max3_f32 v174, v174, v160, v161
	v_max_f32_e32 v174, v174, v175
	v_fmamk_f32 v174, v174, 0x3e38aa3b, v170
	v_sub_f32_e32 v175, v174, v194
	v_cmp_lt_f32_e32 vcc, s33, v175
	s_cbranch_vccnz .Lda_resc0
.Lda_resc0_ret:
	v_sub_f32_e32 v175, v170, v194
	s_waitcnt lgkmcnt(4)
	v_mfma_f32_16x16x32_bf16 v[0:3], v[16:19], v[114:117], v[0:3]
	v_mfma_f32_16x16x32_bf16 v[4:7], v[20:23], v[114:117], v[4:7]
	v_mfma_f32_16x16x32_bf16 v[8:11], v[24:27], v[114:117], v[8:11]
	v_mfma_f32_16x16x32_bf16 v[12:15], v[28:31], v[114:117], v[12:15]
	ds_read_b128 v[16:19], v173 offset:45056
	ds_read_b128 v[20:23], v173 offset:47616
	ds_read_b128 v[24:27], v173 offset:50176
	ds_read_b128 v[28:31], v173 offset:52736
	v_fmamk_f32 v146, v146, 0x3e38aa3b, v175
	v_fmamk_f32 v147, v147, 0x3e38aa3b, v175
	v_fmamk_f32 v148, v148, 0x3e38aa3b, v175
	v_fmamk_f32 v149, v149, 0x3e38aa3b, v175
	v_fmamk_f32 v150, v150, 0x3e38aa3b, v175
	v_fmamk_f32 v151, v151, 0x3e38aa3b, v175
	v_fmamk_f32 v152, v152, 0x3e38aa3b, v175
	v_fmamk_f32 v153, v153, 0x3e38aa3b, v175
	v_fmamk_f32 v154, v154, 0x3e38aa3b, v175
	v_fmamk_f32 v155, v155, 0x3e38aa3b, v175
	v_fmamk_f32 v156, v156, 0x3e38aa3b, v175
	v_fmamk_f32 v157, v157, 0x3e38aa3b, v175
	v_fmamk_f32 v158, v158, 0x3e38aa3b, v175
	v_fmamk_f32 v159, v159, 0x3e38aa3b, v175
	v_fmamk_f32 v160, v160, 0x3e38aa3b, v175
	v_fmamk_f32 v161, v161, 0x3e38aa3b, v175
	v_exp_f32_e32 v146, v146
	v_exp_f32_e32 v147, v147
	v_exp_f32_e32 v148, v148
	v_add_f32_e32 v174, v147, v146
	v_exp_f32_e32 v149, v149
	v_add_f32_e32 v174, v148, v174
	v_exp_f32_e32 v150, v150
	v_add_f32_e32 v174, v149, v174
	v_exp_f32_e32 v151, v151
	v_add_f32_e32 v174, v150, v174
	v_exp_f32_e32 v152, v152
	v_add_f32_e32 v174, v151, v174
	v_exp_f32_e32 v153, v153
	v_add_f32_e32 v174, v152, v174
	v_exp_f32_e32 v154, v154
	v_add_f32_e32 v174, v153, v174
	v_exp_f32_e32 v155, v155
	v_add_f32_e32 v174, v154, v174
	v_exp_f32_e32 v156, v156
	v_add_f32_e32 v174, v155, v174
	v_exp_f32_e32 v157, v157
	v_add_f32_e32 v174, v156, v174
	v_exp_f32_e32 v158, v158
	v_add_f32_e32 v174, v157, v174
	v_exp_f32_e32 v159, v159
	v_add_f32_e32 v174, v158, v174
	v_exp_f32_e32 v160, v160
	v_add_f32_e32 v174, v159, v174
	v_exp_f32_e32 v161, v161
	v_add_f32_e32 v174, v160, v174
	v_cvt_pk_bf16_f32 v146, v146, v147
	v_add_f32_e32 v174, v161, v174
	v_cvt_pk_bf16_f32 v147, v148, v149
	v_add_f32_e32 v192, v192, v174
	v_cvt_pk_bf16_f32 v148, v150, v151
	v_cvt_pk_bf16_f32 v149, v152, v153
	v_cvt_pk_bf16_f32 v150, v154, v155
	v_cvt_pk_bf16_f32 v151, v156, v157
	v_cvt_pk_bf16_f32 v152, v158, v159
	v_cvt_pk_bf16_f32 v153, v160, v161
	ds_read_b128 v[154:157], v173 offset:34880
	ds_read_b128 v[158:161], v173 offset:37440
	v_max3_f32 v174, v0, v1, v2
	v_max3_f32 v175, v3, v4, v5
	v_max3_f32 v174, v174, v6, v7
	v_max3_f32 v175, v175, v8, v9
	v_max3_f32 v174, v174, v10, v11
	v_max3_f32 v175, v175, v12, v13
	v_max3_f32 v174, v174, v14, v15
	v_max_f32_e32 v174, v174, v175
	v_fmamk_f32 v174, v174, 0x3e38aa3b, v170
	v_sub_f32_e32 v175, v174, v171
	v_cmp_lt_f32_e32 vcc, s33, v175
	s_cbranch_vccnz .Lda_resc1
; __device__ __forceinline__ uint2 pack4(float a, float b, float c, float d) { uint2 r; r.x = pk2(a, b); r.y = pk2(c, d); return r; }
; template <int NC, int DQK, int DV, bool CAUSAL, bool PF> ...
;     ...
;         _Pragma("unroll") for (int m = 0; m < 4; ++m) _Pragma("unroll") for (int j = 0; j < 4; ++j) { float pv = __builtin_amdgcn_exp2f(s[m][j] - mm); s[m][j] = pv; psum += pv; }
;       } else {
;         float cc = bb - mrun[c];
;         _Pragma("unroll") for (int m = 0; m < 4; ++m) _Pragma("unroll") for (int j = 0; j < 4; ++j) { float pv = __builtin_amdgcn_exp2f(s[m][j] * scale_log2 + cc); s[m][j] = pv; psum += pv; }
;       }
;       lsum[c] += psum;
;       _Pragma("unroll") for (int k2 = 0; k2 < 2; ++k2) {
;         uint2 lo = pack4(s[2 * k2][0], s[2 * k2][1], s[2 * k2][2], s[2 * k2][3]);
;         uint2 hi = pack4(s[2 * k2 + 1][0], s[2 * k2 + 1][1], s[2 * k2 + 1][2], s[2 * k2 + 1][3]);
;         uint4 pk; pk.x = lo.x; pk.y = lo.y; pk.z = hi.x; pk.w = hi.y;
;         pf[c][k2] = *(bf16x8*)&pk;
;       }
;     }
;     _Pragma("unroll") for (int k2 = 0; k2 < 2; ++k2) _Pragma("unroll") for (int v = 0; v < NVT; ++v) {
;       bf16x8 a = *(const bf16x8*)&Vb[(16 * v + fr) * VLD + 32 * k2 + fq * 8];
;       _Pragma("unroll") for (int c = 0; c < NC; ++c) O[c][v] = __builtin_amdgcn_mfma_f32_16x16x32_bf16(a, pf[c][k2], O[c][v], 0, 0, 0);
;       if ((v & 3) == 3) __builtin_amdgcn_sched_barrier(0);
;     }
.Lda_resc1_ret:
	v_sub_f32_e32 v175, v170, v171
	v_fmamk_f32 v0, v0, 0x3e38aa3b, v175
	v_fmamk_f32 v1, v1, 0x3e38aa3b, v175
	v_fmamk_f32 v2, v2, 0x3e38aa3b, v175
	v_fmamk_f32 v3, v3, 0x3e38aa3b, v175
	v_fmamk_f32 v4, v4, 0x3e38aa3b, v175
	v_fmamk_f32 v5, v5, 0x3e38aa3b, v175
	v_fmamk_f32 v6, v6, 0x3e38aa3b, v175
	v_fmamk_f32 v7, v7, 0x3e38aa3b, v175
	v_fmamk_f32 v8, v8, 0x3e38aa3b, v175
	v_fmamk_f32 v9, v9, 0x3e38aa3b, v175
	v_fmamk_f32 v10, v10, 0x3e38aa3b, v175
	v_fmamk_f32 v11, v11, 0x3e38aa3b, v175
	v_fmamk_f32 v12, v12, 0x3e38aa3b, v175
	v_fmamk_f32 v13, v13, 0x3e38aa3b, v175
	v_fmamk_f32 v14, v14, 0x3e38aa3b, v175
	v_fmamk_f32 v15, v15, 0x3e38aa3b, v175
	v_exp_f32_e32 v0, v0
	v_exp_f32_e32 v1, v1
	v_exp_f32_e32 v2, v2
	v_add_f32_e32 v174, v1, v0
	v_exp_f32_e32 v3, v3
	v_add_f32_e32 v174, v2, v174
	v_exp_f32_e32 v4, v4
	v_add_f32_e32 v174, v3, v174
	v_exp_f32_e32 v5, v5
	v_add_f32_e32 v174, v4, v174
	v_exp_f32_e32 v6, v6
	v_add_f32_e32 v174, v5, v174
	v_exp_f32_e32 v7, v7
	v_add_f32_e32 v174, v6, v174
	v_exp_f32_e32 v8, v8
	v_add_f32_e32 v174, v7, v174
	v_exp_f32_e32 v9, v9
	v_add_f32_e32 v174, v8, v174
	v_exp_f32_e32 v10, v10
	v_add_f32_e32 v174, v9, v174
	v_exp_f32_e32 v11, v11
	v_add_f32_e32 v174, v10, v174
	v_exp_f32_e32 v12, v12
	v_add_f32_e32 v174, v11, v174
	v_exp_f32_e32 v13, v13
	v_add_f32_e32 v174, v12, v174
	v_exp_f32_e32 v14, v14
	v_add_f32_e32 v174, v13, v174
	v_exp_f32_e32 v15, v15
	v_add_f32_e32 v174, v14, v174
	v_cvt_pk_bf16_f32 v0, v0, v1
	v_add_f32_e32 v174, v15, v174
	v_cvt_pk_bf16_f32 v1, v2, v3
	v_add_f32_e32 v191, v191, v174
	v_cvt_pk_bf16_f32 v2, v4, v5
	v_cvt_pk_bf16_f32 v3, v6, v7
	v_cvt_pk_bf16_f32 v4, v8, v9
	v_cvt_pk_bf16_f32 v5, v10, v11
	v_cvt_pk_bf16_f32 v6, v12, v13
	v_cvt_pk_bf16_f32 v7, v14, v15
	ds_read_b128 v[8:11], v173 offset:40000
	ds_read_b128 v[12:15], v173 offset:42560
	s_waitcnt lgkmcnt(10)
	v_mfma_f32_16x16x32_bf16 v[106:109], v[122:125], v[146:149], v[106:109]
	v_mfma_f32_16x16x32_bf16 v[110:113], v[122:125], v[0:3], v[110:113]
	v_mfma_f32_16x16x32_bf16 v[98:101], v[126:129], v[146:149], v[98:101]
	v_mfma_f32_16x16x32_bf16 v[102:105], v[126:129], v[0:3], v[102:105]
	s_waitcnt lgkmcnt(8)
	v_mfma_f32_16x16x32_bf16 v[90:93], v[130:133], v[146:149], v[90:93]
	v_mfma_f32_16x16x32_bf16 v[94:97], v[130:133], v[0:3], v[94:97]
	v_mfma_f32_16x16x32_bf16 v[78:81], v[142:145], v[146:149], v[78:81]
	v_mfma_f32_16x16x32_bf16 v[74:77], v[142:145], v[0:3], v[74:77]
	ds_read_b128 v[122:125], v173 offset:45120
	ds_read_b128 v[126:129], v173 offset:47680
	ds_read_b128 v[130:133], v173 offset:50240
	ds_read_b128 v[142:145], v173 offset:52800
	s_waitcnt lgkmcnt(10)
	v_mfma_f32_16x16x32_bf16 v[62:65], v[16:19], v[146:149], v[62:65]
	v_mfma_f32_16x16x32_bf16 v[70:73], v[16:19], v[0:3], v[70:73]
	v_mfma_f32_16x16x32_bf16 v[50:53], v[20:23], v[146:149], v[50:53]
	v_mfma_f32_16x16x32_bf16 v[66:69], v[20:23], v[0:3], v[66:69]
	s_waitcnt lgkmcnt(8)
	v_mfma_f32_16x16x32_bf16 v[54:57], v[24:27], v[146:149], v[54:57]
	v_mfma_f32_16x16x32_bf16 v[58:61], v[24:27], v[0:3], v[58:61]
	v_mfma_f32_16x16x32_bf16 v[82:85], v[28:31], v[146:149], v[82:85]
	v_mfma_f32_16x16x32_bf16 v[86:89], v[28:31], v[0:3], v[86:89]
	s_waitcnt lgkmcnt(6)
	v_mfma_f32_16x16x32_bf16 v[106:109], v[154:157], v[150:153], v[106:109]
	v_mfma_f32_16x16x32_bf16 v[110:113], v[154:157], v[4:7], v[110:113]
	v_mfma_f32_16x16x32_bf16 v[98:101], v[158:161], v[150:153], v[98:101]
	v_mfma_f32_16x16x32_bf16 v[102:105], v[158:161], v[4:7], v[102:105]
	s_waitcnt lgkmcnt(4)
	v_mfma_f32_16x16x32_bf16 v[90:93], v[8:11], v[150:153], v[90:93]
	v_mfma_f32_16x16x32_bf16 v[94:97], v[8:11], v[4:7], v[94:97]
	v_mfma_f32_16x16x32_bf16 v[78:81], v[12:15], v[150:153], v[78:81]
	v_mfma_f32_16x16x32_bf16 v[74:77], v[12:15], v[4:7], v[74:77]
	s_waitcnt lgkmcnt(2)
	v_mfma_f32_16x16x32_bf16 v[62:65], v[122:125], v[150:153], v[62:65]
	v_mfma_f32_16x16x32_bf16 v[70:73], v[122:125], v[4:7], v[70:73]
	v_mfma_f32_16x16x32_bf16 v[50:53], v[126:129], v[150:153], v[50:53]
	v_mfma_f32_16x16x32_bf16 v[66:69], v[126:129], v[4:7], v[66:69]
	s_waitcnt lgkmcnt(0)
	v_mfma_f32_16x16x32_bf16 v[54:57], v[130:133], v[150:153], v[54:57]
	v_mfma_f32_16x16x32_bf16 v[58:61], v[130:133], v[4:7], v[58:61]
	v_mfma_f32_16x16x32_bf16 v[82:85], v[142:145], v[150:153], v[82:85]
	v_mfma_f32_16x16x32_bf16 v[86:89], v[142:145], v[4:7], v[86:89]
	s_branch .LBB0_1784

; template <int NC, int DQK, int DV, bool CAUSAL, bool PF> ...
;     ...
;       _Pragma("unroll") for (int ks = 0; ks < NKS; ++ks) _Pragma("unroll") for (int m = 0; m < 4; ++m) {
;         bf16x8 a = *(const bf16x8*)&Kb[(16 * m + fr) * KLD + c * DQK + ks * 32 + fq * 8];
;         s[m] = __builtin_amdgcn_mfma_f32_16x16x32_bf16(a, qf[c][ks], s[m], 0, 0, 0);
;       }
;       constexpr float THR = 8.f;
;       float tnew, psum = 0.f;
;       if (general) {
;         float tmax = -1e30f;
;         _Pragma("unroll") for (int m = 0; m < 4; ++m) _Pragma("unroll") for (int j = 0; j < 4; ++j) {
;           float v = s[m][j] * scale_log2 + bv[m][j];
;           s[m][j] = v; tmax = fmaxf(tmax, v);
;         }
;         tnew = tmax;
;       } else {
;         float rmax = fmaxf(fmaxf(s[0][0], s[0][1]), fmaxf(s[0][2], s[0][3]));
;         _Pragma("unroll") for (int m = 1; m < 4; ++m) rmax = fmaxf(rmax, fmaxf(fmaxf(s[m][0], s[m][1]), fmaxf(s[m][2], s[m][3])));
;         tnew = rmax * scale_log2 + bb;
;       }
;       if (__builtin_amdgcn_ballot_w64(tnew - mrun[c] > THR) != 0ull) {
;         tnew = fmaxf(tnew, sx<16>(tnew, lane)); tnew = fmaxf(tnew, sx<32>(tnew, lane));
;     ...
;     _Pragma("unroll") for (int k2 = 0; k2 < 2; ++k2) _Pragma("unroll") for (int v = 0; v < NVT; ++v) {
;       bf16x8 a = *(const bf16x8*)&Vb[(16 * v + fr) * VLD + 32 * k2 + fq * 8];
;       _Pragma("unroll") for (int c = 0; c < NC; ++c) O[c][v] = __builtin_amdgcn_mfma_f32_16x16x32_bf16(a, pf[c][k2], O[c][v], 0, 0, 0);
;       if ((v & 3) == 3) __builtin_amdgcn_sched_barrier(0);
.Ldb_fastB:
	v_add3_u32 v172, s38, v32, v195
	s_cmp_eq_u32 s34, 0
	s_cbranch_scc1 .Ldb_B_nopend
	s_sub_i32 s8, s37, 0x5000
	s_cmp_lt_i32 s8, 0
	s_cselect_b32 s8, 0xa000, s8
	v_add3_u32 v173, s8, v32, v193
	ds_read_b128 v[0:3], v173 offset:34816
	ds_read_b128 v[4:7], v173 offset:37376
	ds_read_b128 v[8:11], v173 offset:39936
	ds_read_b128 v[12:15], v173 offset:42496
	ds_read_b128 v[16:19], v173 offset:45056
	ds_read_b128 v[20:23], v173 offset:47616
	ds_read_b128 v[24:27], v173 offset:50176
	ds_read_b128 v[28:31], v173 offset:52736
	ds_read_b128 v[122:125], v173 offset:34880
	ds_read_b128 v[126:129], v173 offset:37440
	ds_read_b128 v[130:133], v173 offset:40000
	ds_read_b128 v[142:145], v173 offset:42560
	s_waitcnt lgkmcnt(10)
	v_mfma_f32_16x16x32_bf16 v[106:109], v[0:3], v[146:149], v[106:109]
	v_mfma_f32_16x16x32_bf16 v[110:113], v[0:3], v[154:157], v[110:113]
	v_mfma_f32_16x16x32_bf16 v[98:101], v[4:7], v[146:149], v[98:101]
	v_mfma_f32_16x16x32_bf16 v[102:105], v[4:7], v[154:157], v[102:105]
	s_waitcnt lgkmcnt(8)
	v_mfma_f32_16x16x32_bf16 v[90:93], v[8:11], v[146:149], v[90:93]
	v_mfma_f32_16x16x32_bf16 v[94:97], v[8:11], v[154:157], v[94:97]
	v_mfma_f32_16x16x32_bf16 v[78:81], v[12:15], v[146:149], v[78:81]
	v_mfma_f32_16x16x32_bf16 v[74:77], v[12:15], v[154:157], v[74:77]
	ds_read_b128 v[0:3], v173 offset:45120
	ds_read_b128 v[4:7], v173 offset:47680
	ds_read_b128 v[8:11], v173 offset:50240
	ds_read_b128 v[12:15], v173 offset:52800
	s_waitcnt lgkmcnt(10)
	v_mfma_f32_16x16x32_bf16 v[62:65], v[16:19], v[146:149], v[62:65]
	v_mfma_f32_16x16x32_bf16 v[70:73], v[16:19], v[154:157], v[70:73]
	v_mfma_f32_16x16x32_bf16 v[50:53], v[20:23], v[146:149], v[50:53]
	v_mfma_f32_16x16x32_bf16 v[66:69], v[20:23], v[154:157], v[66:69]
	s_waitcnt lgkmcnt(8)
	v_mfma_f32_16x16x32_bf16 v[54:57], v[24:27], v[146:149], v[54:57]
	v_mfma_f32_16x16x32_bf16 v[58:61], v[24:27], v[154:157], v[58:61]
	v_mfma_f32_16x16x32_bf16 v[82:85], v[28:31], v[146:149], v[82:85]
	v_mfma_f32_16x16x32_bf16 v[86:89], v[28:31], v[154:157], v[86:89]
	ds_read_b128 v[16:19], v172 offset:64
	ds_read_b128 v[20:23], v172 offset:4416
	ds_read_b128 v[24:27], v172 offset:8768
	ds_read_b128 v[28:31], v172 offset:13120
	s_waitcnt lgkmcnt(10)
	v_mfma_f32_16x16x32_bf16 v[106:109], v[122:125], v[150:153], v[106:109]
	v_mfma_f32_16x16x32_bf16 v[110:113], v[122:125], v[158:161], v[110:113]
	v_mfma_f32_16x16x32_bf16 v[98:101], v[126:129], v[150:153], v[98:101]
	v_mfma_f32_16x16x32_bf16 v[102:105], v[126:129], v[158:161], v[102:105]
	s_waitcnt lgkmcnt(8)
	v_mfma_f32_16x16x32_bf16 v[90:93], v[130:133], v[150:153], v[90:93]
	v_mfma_f32_16x16x32_bf16 v[94:97], v[130:133], v[158:161], v[94:97]
	v_mfma_f32_16x16x32_bf16 v[78:81], v[142:145], v[150:153], v[78:81]
	v_mfma_f32_16x16x32_bf16 v[74:77], v[142:145], v[158:161], v[74:77]
	ds_read_b128 v[122:125], v172
	ds_read_b128 v[126:129], v172 offset:4352
	ds_read_b128 v[130:133], v172 offset:8704
	ds_read_b128 v[142:145], v172 offset:13056
	s_waitcnt lgkmcnt(10)
	v_mfma_f32_16x16x32_bf16 v[62:65], v[0:3], v[150:153], v[62:65]
	v_mfma_f32_16x16x32_bf16 v[70:73], v[0:3], v[158:161], v[70:73]
	v_mfma_f32_16x16x32_bf16 v[50:53], v[4:7], v[150:153], v[50:53]
	v_mfma_f32_16x16x32_bf16 v[66:69], v[4:7], v[158:161], v[66:69]
	s_waitcnt lgkmcnt(8)
	v_mfma_f32_16x16x32_bf16 v[54:57], v[8:11], v[150:153], v[54:57]
	v_mfma_f32_16x16x32_bf16 v[58:61], v[8:11], v[158:161], v[58:61]
	v_mfma_f32_16x16x32_bf16 v[82:85], v[12:15], v[150:153], v[82:85]
	v_mfma_f32_16x16x32_bf16 v[86:89], v[12:15], v[158:161], v[86:89]
	ds_read_b128 v[0:3], v172 offset:128
	ds_read_b128 v[4:7], v172 offset:4480
	ds_read_b128 v[8:11], v172 offset:8832
	ds_read_b128 v[12:15], v172 offset:13184
	s_branch .Ldb_B_qk
.Ldb_B_nopend:
	ds_read_b128 v[16:19], v172 offset:64
	ds_read_b128 v[20:23], v172 offset:4416
	ds_read_b128 v[24:27], v172 offset:8768
	ds_read_b128 v[28:31], v172 offset:13120
	ds_read_b128 v[122:125], v172
	ds_read_b128 v[126:129], v172 offset:4352
	ds_read_b128 v[130:133], v172 offset:8704
	ds_read_b128 v[142:145], v172 offset:13056
	ds_read_b128 v[0:3], v172 offset:128
	ds_read_b128 v[4:7], v172 offset:4480
	ds_read_b128 v[8:11], v172 offset:8832
	ds_read_b128 v[12:15], v172 offset:13184
.Ldb_B_qk:
	s_waitcnt lgkmcnt(4)
	v_mfma_f32_16x16x32_bf16 v[122:125], v[122:125], v[138:141], 0
	v_mfma_f32_16x16x32_bf16 v[126:129], v[126:129], v[138:141], 0
	v_mfma_f32_16x16x32_bf16 v[130:133], v[130:133], v[138:141], 0
	v_mfma_f32_16x16x32_bf16 v[142:145], v[142:145], v[138:141], 0
	v_mfma_f32_16x16x32_bf16 v[122:125], v[16:19], v[134:137], v[122:125]
	v_mfma_f32_16x16x32_bf16 v[126:129], v[20:23], v[134:137], v[126:129]
	v_mfma_f32_16x16x32_bf16 v[130:133], v[24:27], v[134:137], v[130:133]
	v_mfma_f32_16x16x32_bf16 v[142:145], v[28:31], v[134:137], v[142:145]
	ds_read_b128 v[16:19], v172 offset:192
	ds_read_b128 v[20:23], v172 offset:4544
	ds_read_b128 v[24:27], v172 offset:8896
	ds_read_b128 v[28:31], v172 offset:13248
	s_waitcnt lgkmcnt(4)
	v_mfma_f32_16x16x32_bf16 v[0:3], v[0:3], v[118:121], 0
	v_mfma_f32_16x16x32_bf16 v[4:7], v[4:7], v[118:121], 0
	v_mfma_f32_16x16x32_bf16 v[8:11], v[8:11], v[118:121], 0
	v_mfma_f32_16x16x32_bf16 v[12:15], v[12:15], v[118:121], 0
	v_max3_f32 v174, v122, v123, v124
	v_max3_f32 v175, v125, v126, v127
	v_max3_f32 v174, v174, v128, v129
	v_max3_f32 v175, v175, v130, v131
	v_max3_f32 v174, v174, v132, v133
	v_max3_f32 v175, v175, v142, v143
	v_max3_f32 v174, v174, v144, v145
	v_max_f32_e32 v174, v174, v175
	v_fmamk_f32 v174, v174, 0x3e38aa3b, v170
	v_sub_f32_e32 v175, v174, v194
	v_cmp_lt_f32_e32 vcc, s33, v175
	s_cbranch_vccnz .Ldb_resc0
; __device__ __forceinline__ uint2 pack4(float a, float b, float c, float d) { uint2 r; r.x = pk2(a, b); r.y = pk2(c, d); return r; }
; template <int NC, int DQK, int DV, bool CAUSAL, bool PF> ...
;     ...
;       if (__builtin_amdgcn_ballot_w64(tnew - mrun[c] > THR) != 0ull) {
;         tnew = fmaxf(tnew, sx<16>(tnew, lane)); tnew = fmaxf(tnew, sx<32>(tnew, lane));
;         float mnew = fmaxf(mrun[c], tnew);
;         float alpha = __builtin_amdgcn_exp2f(mrun[c] - mnew);
;         mrun[c] = mnew; lsum[c] *= alpha;
;         _Pragma("unroll") for (int v = 0; v < NVT; ++v) _Pragma("unroll") for (int j = 0; j < 4; ++j) O[c][v][j] *= alpha;
;       }
;       if (general) {
;         float mm = mrun[c];
;         _Pragma("unroll") for (int m = 0; m < 4; ++m) _Pragma("unroll") for (int j = 0; j < 4; ++j) { float pv = __builtin_amdgcn_exp2f(s[m][j] - mm); s[m][j] = pv; psum += pv; }
;       } else {
;         float cc = bb - mrun[c];
;         _Pragma("unroll") for (int m = 0; m < 4; ++m) _Pragma("unroll") for (int j = 0; j < 4; ++j) { float pv = __builtin_amdgcn_exp2f(s[m][j] * scale_log2 + cc); s[m][j] = pv; psum += pv; }
;       }
;       lsum[c] += psum;
;       _Pragma("unroll") for (int k2 = 0; k2 < 2; ++k2) {
;         uint2 lo = pack4(s[2 * k2][0], s[2 * k2][1], s[2 * k2][2], s[2 * k2][3]);
;         uint2 hi = pack4(s[2 * k2 + 1][0], s[2 * k2 + 1][1], s[2 * k2 + 1][2], s[2 * k2 + 1][3]);
;         uint4 pk; pk.x = lo.x; pk.y = lo.y; pk.z = hi.x; pk.w = hi.y;
;         pf[c][k2] = *(bf16x8*)&pk;
;       }
.Ldb_resc0_ret:
	v_sub_f32_e32 v175, v170, v194
	s_waitcnt lgkmcnt(0)
	v_mfma_f32_16x16x32_bf16 v[0:3], v[16:19], v[114:117], v[0:3]
	v_mfma_f32_16x16x32_bf16 v[4:7], v[20:23], v[114:117], v[4:7]
	v_mfma_f32_16x16x32_bf16 v[8:11], v[24:27], v[114:117], v[8:11]
	v_mfma_f32_16x16x32_bf16 v[12:15], v[28:31], v[114:117], v[12:15]
	v_fmamk_f32 v122, v122, 0x3e38aa3b, v175
	v_fmamk_f32 v123, v123, 0x3e38aa3b, v175
	v_fmamk_f32 v124, v124, 0x3e38aa3b, v175
	v_fmamk_f32 v125, v125, 0x3e38aa3b, v175
	v_fmamk_f32 v126, v126, 0x3e38aa3b, v175
	v_fmamk_f32 v127, v127, 0x3e38aa3b, v175
	v_fmamk_f32 v128, v128, 0x3e38aa3b, v175
	v_fmamk_f32 v129, v129, 0x3e38aa3b, v175
	v_fmamk_f32 v130, v130, 0x3e38aa3b, v175
	v_fmamk_f32 v131, v131, 0x3e38aa3b, v175
	v_fmamk_f32 v132, v132, 0x3e38aa3b, v175
	v_fmamk_f32 v133, v133, 0x3e38aa3b, v175
	v_fmamk_f32 v142, v142, 0x3e38aa3b, v175
	v_fmamk_f32 v143, v143, 0x3e38aa3b, v175
	v_fmamk_f32 v144, v144, 0x3e38aa3b, v175
	v_fmamk_f32 v145, v145, 0x3e38aa3b, v175
	v_exp_f32_e32 v122, v122
	v_exp_f32_e32 v123, v123
	v_exp_f32_e32 v124, v124
	v_add_f32_e32 v174, v123, v122
	v_exp_f32_e32 v125, v125
	v_add_f32_e32 v174, v124, v174
	v_exp_f32_e32 v126, v126
	v_add_f32_e32 v174, v125, v174
	v_exp_f32_e32 v127, v127
	v_add_f32_e32 v174, v126, v174
	v_exp_f32_e32 v128, v128
	v_add_f32_e32 v174, v127, v174
	v_exp_f32_e32 v129, v129
	v_add_f32_e32 v174, v128, v174
	v_exp_f32_e32 v130, v130
	v_add_f32_e32 v174, v129, v174
	v_exp_f32_e32 v131, v131
	v_add_f32_e32 v174, v130, v174
	v_exp_f32_e32 v132, v132
	v_add_f32_e32 v174, v131, v174
	v_exp_f32_e32 v133, v133
	v_add_f32_e32 v174, v132, v174
	v_exp_f32_e32 v142, v142
	v_add_f32_e32 v174, v133, v174
	v_exp_f32_e32 v143, v143
	v_add_f32_e32 v174, v142, v174
	v_exp_f32_e32 v144, v144
	v_add_f32_e32 v174, v143, v174
	v_exp_f32_e32 v145, v145
	v_add_f32_e32 v174, v144, v174
	v_cvt_pk_bf16_f32 v146, v122, v123
	v_add_f32_e32 v174, v145, v174
	v_cvt_pk_bf16_f32 v147, v124, v125
	v_add_f32_e32 v192, v192, v174
	v_cvt_pk_bf16_f32 v148, v126, v127
	v_cvt_pk_bf16_f32 v149, v128, v129
	v_cvt_pk_bf16_f32 v150, v130, v131
	v_cvt_pk_bf16_f32 v151, v132, v133
	v_cvt_pk_bf16_f32 v152, v142, v143
	v_cvt_pk_bf16_f32 v153, v144, v145
	v_max3_f32 v174, v0, v1, v2
	v_max3_f32 v175, v3, v4, v5
	v_max3_f32 v174, v174, v6, v7
	v_max3_f32 v175, v175, v8, v9
	v_max3_f32 v174, v174, v10, v11
	v_max3_f32 v175, v175, v12, v13
	v_max3_f32 v174, v174, v14, v15
	v_max_f32_e32 v174, v174, v175
	v_fmamk_f32 v174, v174, 0x3e38aa3b, v170
	v_sub_f32_e32 v175, v174, v171
	v_cmp_lt_f32_e32 vcc, s33, v175
	s_cbranch_vccnz .Ldb_resc1
.Ldb_resc1_ret:
	v_sub_f32_e32 v175, v170, v171
	v_fmamk_f32 v0, v0, 0x3e38aa3b, v175
	v_fmamk_f32 v1, v1, 0x3e38aa3b, v175
	v_fmamk_f32 v2, v2, 0x3e38aa3b, v175
	v_fmamk_f32 v3, v3, 0x3e38aa3b, v175
	v_fmamk_f32 v4, v4, 0x3e38aa3b, v175
	v_fmamk_f32 v5, v5, 0x3e38aa3b, v175
	v_fmamk_f32 v6, v6, 0x3e38aa3b, v175
	v_fmamk_f32 v7, v7, 0x3e38aa3b, v175
	v_fmamk_f32 v8, v8, 0x3e38aa3b, v175
	v_fmamk_f32 v9, v9, 0x3e38aa3b, v175
	v_fmamk_f32 v10, v10, 0x3e38aa3b, v175
	v_fmamk_f32 v11, v11, 0x3e38aa3b, v175
	v_fmamk_f32 v12, v12, 0x3e38aa3b, v175
	v_fmamk_f32 v13, v13, 0x3e38aa3b, v175
	v_fmamk_f32 v14, v14, 0x3e38aa3b, v175
	v_fmamk_f32 v15, v15, 0x3e38aa3b, v175
	v_exp_f32_e32 v0, v0
	v_exp_f32_e32 v1, v1
	v_exp_f32_e32 v2, v2
	v_add_f32_e32 v174, v1, v0
	v_exp_f32_e32 v3, v3
	v_add_f32_e32 v174, v2, v174
	v_exp_f32_e32 v4, v4
	v_add_f32_e32 v174, v3, v174
	v_exp_f32_e32 v5, v5
	v_add_f32_e32 v174, v4, v174
	v_exp_f32_e32 v6, v6
	v_add_f32_e32 v174, v5, v174
	v_exp_f32_e32 v7, v7
	v_add_f32_e32 v174, v6, v174
	v_exp_f32_e32 v8, v8
	v_add_f32_e32 v174, v7, v174
	v_exp_f32_e32 v9, v9
	v_add_f32_e32 v174, v8, v174
	v_exp_f32_e32 v10, v10
	v_add_f32_e32 v174, v9, v174
	v_exp_f32_e32 v11, v11
	v_add_f32_e32 v174, v10, v174
	v_exp_f32_e32 v12, v12
	v_add_f32_e32 v174, v11, v174
	v_exp_f32_e32 v13, v13
	v_add_f32_e32 v174, v12, v174
	v_exp_f32_e32 v14, v14
	v_add_f32_e32 v174, v13, v174
	v_exp_f32_e32 v15, v15
	v_add_f32_e32 v174, v14, v174
	v_cvt_pk_bf16_f32 v154, v0, v1
	v_add_f32_e32 v174, v15, v174
	v_cvt_pk_bf16_f32 v155, v2, v3
	v_add_f32_e32 v191, v191, v174
	v_cvt_pk_bf16_f32 v156, v4, v5
	v_cvt_pk_bf16_f32 v157, v6, v7
	v_cvt_pk_bf16_f32 v158, v8, v9
	v_cvt_pk_bf16_f32 v159, v10, v11
	v_cvt_pk_bf16_f32 v160, v12, v13
	v_cvt_pk_bf16_f32 v161, v14, v15
	s_branch .LBB0_1784

; #define FA_PREFETCH(kt_) do { int k0_ = (kt_) * 64; \
;     _Pragma("unroll") for (int i = 0; i < KPT; ++i) kreg[i] = __builtin_amdgcn_raw_buffer_load_b128(rsK, kvo[i], k0_ * k_stride * 2, 0); \
;     _Pragma("unroll") for (int i = 0; i < VPT; ++i) vreg[i] = __builtin_amdgcn_raw_buffer_load_b128(rsV, vvo[i], k0_ * 2, 0); } while (0)
; #define FA_PREFETCH_NEXT() do { \
;     _Pragma("unroll") for (int i = 0; i < KPT; ++i) kreg[i] = __builtin_amdgcn_raw_buffer_load_b128(rsNK, kvo[i], 0, 0); \
;     _Pragma("unroll") for (int i = 0; i < VPT; ++i) vreg[i] = __builtin_amdgcn_raw_buffer_load_b128(rsNV, vvo[i], 0, 0); } while (0)
; template <int NC, int DQK, int DV, bool CAUSAL, bool PF> ...
;     ...
;   for (int kt = 0; kt < nkt; ++kt) {
;     if (!PF) FA_PREFETCH(kt);
;     u16* Kb = Ks + (kt & 1) * KBUF; u16* Vb = Vs + (kt & 1) * VBUF;
;     _Pragma("unroll") for (int i = 0; i < KPT; ++i) { int id = tid + i * 512, row = id / KCH, cc = id % KCH; *(u32x4*)&Kb[row * KLD + cc * 8] = kreg[i]; }
;     _Pragma("unroll") for (int i = 0; i < VPT; ++i) {
;       int id = tid + i * 512, row = id >> 3, cc = id & 7;
;       int pos = 32 * (cc >> 2) + 16 * (cc & 1) + 4 * ((cc >> 1) & 1);
;       uint2 lo2, hi2; lo2.x = vreg[i][0]; lo2.y = vreg[i][1]; hi2.x = vreg[i][2]; hi2.y = vreg[i][3];
;       *(uint2*)&Vb[row * VLD + pos] = lo2; *(uint2*)&Vb[row * VLD + pos + 8] = hi2;
;     }
;     __syncthreads();
;     if (PF && kt + 1 < nkt) FA_PREFETCH(kt + 1); else if (PF && has_next_item) FA_PREFETCH_NEXT();
;     ...
;     _Pragma("unroll") for (int k2 = 0; k2 < 2; ++k2) _Pragma("unroll") for (int v = 0; v < NVT; ++v) {
;       bf16x8 a = *(const bf16x8*)&Vb[(16 * v + fr) * VLD + 32 * k2 + fq * 8];
;       _Pragma("unroll") for (int c = 0; c < NC; ++c) O[c][v] = __builtin_amdgcn_mfma_f32_16x16x32_bf16(a, pf[c][k2], O[c][v], 0, 0, 0);
;       if ((v & 3) == 3) __builtin_amdgcn_sched_barrier(0);
;     }
.Ldb_flushB:
	s_sub_i32 s8, s37, 0x5000
	s_cmp_lt_i32 s8, 0
	s_cselect_b32 s8, 0xa000, s8
	v_add3_u32 v173, s8, v32, v193
	ds_read_b128 v[0:3], v173 offset:34816
	ds_read_b128 v[4:7], v173 offset:37376
	ds_read_b128 v[8:11], v173 offset:39936
	ds_read_b128 v[12:15], v173 offset:42496
	ds_read_b128 v[16:19], v173 offset:45056
	ds_read_b128 v[20:23], v173 offset:47616
	ds_read_b128 v[24:27], v173 offset:50176
	ds_read_b128 v[28:31], v173 offset:52736
	ds_read_b128 v[122:125], v173 offset:34880
	ds_read_b128 v[126:129], v173 offset:37440
	ds_read_b128 v[130:133], v173 offset:40000
	ds_read_b128 v[142:145], v173 offset:42560
	s_waitcnt lgkmcnt(10)
	v_mfma_f32_16x16x32_bf16 v[106:109], v[0:3], v[146:149], v[106:109]
	v_mfma_f32_16x16x32_bf16 v[110:113], v[0:3], v[154:157], v[110:113]
	v_mfma_f32_16x16x32_bf16 v[98:101], v[4:7], v[146:149], v[98:101]
	v_mfma_f32_16x16x32_bf16 v[102:105], v[4:7], v[154:157], v[102:105]
	s_waitcnt lgkmcnt(8)
	v_mfma_f32_16x16x32_bf16 v[90:93], v[8:11], v[146:149], v[90:93]
	v_mfma_f32_16x16x32_bf16 v[94:97], v[8:11], v[154:157], v[94:97]
	v_mfma_f32_16x16x32_bf16 v[78:81], v[12:15], v[146:149], v[78:81]
	v_mfma_f32_16x16x32_bf16 v[74:77], v[12:15], v[154:157], v[74:77]
	ds_read_b128 v[0:3], v173 offset:45120
	ds_read_b128 v[4:7], v173 offset:47680
	ds_read_b128 v[8:11], v173 offset:50240
	ds_read_b128 v[12:15], v173 offset:52800
	s_waitcnt lgkmcnt(10)
	v_mfma_f32_16x16x32_bf16 v[62:65], v[16:19], v[146:149], v[62:65]
	v_mfma_f32_16x16x32_bf16 v[70:73], v[16:19], v[154:157], v[70:73]
	v_mfma_f32_16x16x32_bf16 v[50:53], v[20:23], v[146:149], v[50:53]
	v_mfma_f32_16x16x32_bf16 v[66:69], v[20:23], v[154:157], v[66:69]
	s_waitcnt lgkmcnt(8)
	v_mfma_f32_16x16x32_bf16 v[54:57], v[24:27], v[146:149], v[54:57]
	v_mfma_f32_16x16x32_bf16 v[58:61], v[24:27], v[154:157], v[58:61]
	v_mfma_f32_16x16x32_bf16 v[82:85], v[28:31], v[146:149], v[82:85]
	v_mfma_f32_16x16x32_bf16 v[86:89], v[28:31], v[154:157], v[86:89]
	s_waitcnt lgkmcnt(6)
	v_mfma_f32_16x16x32_bf16 v[106:109], v[122:125], v[150:153], v[106:109]
	v_mfma_f32_16x16x32_bf16 v[110:113], v[122:125], v[158:161], v[110:113]
	v_mfma_f32_16x16x32_bf16 v[98:101], v[126:129], v[150:153], v[98:101]
	v_mfma_f32_16x16x32_bf16 v[102:105], v[126:129], v[158:161], v[102:105]
	s_waitcnt lgkmcnt(4)
	v_mfma_f32_16x16x32_bf16 v[90:93], v[130:133], v[150:153], v[90:93]
	v_mfma_f32_16x16x32_bf16 v[94:97], v[130:133], v[158:161], v[94:97]
	v_mfma_f32_16x16x32_bf16 v[78:81], v[142:145], v[150:153], v[78:81]
	v_mfma_f32_16x16x32_bf16 v[74:77], v[142:145], v[158:161], v[74:77]
	s_waitcnt lgkmcnt(2)
	v_mfma_f32_16x16x32_bf16 v[62:65], v[0:3], v[150:153], v[62:65]
	v_mfma_f32_16x16x32_bf16 v[70:73], v[0:3], v[158:161], v[70:73]
	v_mfma_f32_16x16x32_bf16 v[50:53], v[4:7], v[150:153], v[50:53]
	v_mfma_f32_16x16x32_bf16 v[66:69], v[4:7], v[158:161], v[66:69]
	s_waitcnt lgkmcnt(0)
	v_mfma_f32_16x16x32_bf16 v[54:57], v[8:11], v[150:153], v[54:57]
	v_mfma_f32_16x16x32_bf16 v[58:61], v[8:11], v[158:161], v[58:61]
	v_mfma_f32_16x16x32_bf16 v[82:85], v[12:15], v[150:153], v[82:85]
	v_mfma_f32_16x16x32_bf16 v[86:89], v[12:15], v[158:161], v[86:89]
	v_cmp_gt_i32_e32 vcc, s35, v202
	s_branch .Lda_gen_cont
.LBB0_1808:
	s_add_i32 s28, s28, s70
	s_cmpk_gt_i32 s28, 0x7ff
	s_cselect_b64 s[12:13], -1, 0
	s_and_b32 s0, s30, 1
	s_mul_i32 s1, s0, 0x4400
	s_add_i32 s34, s1, 0
	v_add3_u32 v0, s34, v210, v204
	s_mul_hi_u32 s0, s30, 0xaaaaaaab
	s_lshr_b32 s0, s0, 1
	s_mul_i32 s0, s0, 3
	s_sub_i32 s0, s30, s0
	s_mul_i32 s0, s0, 0x5000
	s_waitcnt vmcnt(3)
	ds_write_b128 v0, v[34:37]
	v_add3_u32 v0, s34, v209, v205
	s_mov_b32 s31, s0
	s_waitcnt vmcnt(2)
	ds_write_b128 v0, v[38:41]
	v_lshl_add_u32 v0, v206, 1, s31
	v_add3_u32 v0, v0, v211, v212
	v_add_u32_e32 v1, v0, v208
	v_add_u32_e32 v0, v0, v207
	v_add_u32_e32 v1, 0x8800, v1
	v_add_u32_e32 v0, 0x8800, v0
	s_and_b64 vcc, exec, s[12:13]
	s_waitcnt vmcnt(0)
	ds_write2_b64 v1, v[42:43], v[44:45] offset1:2
	ds_write2_b64 v0, v[46:47], v[48:49] offset1:2
	s_waitcnt lgkmcnt(0)
	s_barrier
	s_cbranch_vccnz .LBB0_1810
	s_ashr_i32 s0, s28, 9
	s_ashr_i32 s1, s0, 31
	s_lshl_b64 s[6:7], s[0:1], 24
	s_add_u32 s1, s22, s6
	s_addc_u32 s6, s23, s7
	s_lshl_b32 s7, s28, 7
	s_and_b32 s7, s7, 0x380
	s_lshl_b32 s8, s7, 1
	s_add_u32 s80, s1, s8
	s_addc_u32 s6, s6, 0
	s_lshl_b32 s0, s0, 10
	s_or_b32 s0, s0, s7
	s_ashr_i32 s1, s0, 31
	s_lshl_b64 s[0:1], s[0:1], 14
	v_readlane_b32 s36, v254, 26
	v_readlane_b32 s39, v254, 29
	s_add_u32 s36, s24, s0
	v_readlane_b32 s37, v254, 27
	v_readlane_b32 s38, v254, 28
	s_addc_u32 s0, s25, s1
	s_and_b32 s81, s6, 0xffff
	s_mov_b32 s83, s39
	s_and_b32 s37, s0, 0xffff
	s_mov_b32 s38, s82
	buffer_load_dwordx4 v[34:37], v198, s[80:83], 0 offen
	buffer_load_dwordx4 v[38:41], v199, s[80:83], 0 offen
	buffer_load_dwordx4 v[42:45], v201, s[36:39], 0 offen
	buffer_load_dwordx4 v[46:49], v200, s[36:39], 0 offen
	s_mov_b32 s7, s39
	v_writelane_b32 v254, s4, 26
	s_nop 1
	v_writelane_b32 v254, s5, 27
	v_writelane_b32 v254, s6, 28
	v_writelane_b32 v254, s7, 29

; __device__ __forceinline__ float silu_f(float x) { return x * sigmoid_f(x); }
; __device__ __forceinline__ uint2 pack4(float a, float b, float c, float d) { uint2 r; r.x = pk2(a, b); r.y = pk2(c, d); return r; }
; __device__ __forceinline__ float row_rs(const float* part, int row) {
;   const float4* q = (const float4*)(part + (long)row * 8);
;   float4 a = q[0], b = q[1];
;   float s = ((a.x + a.y) + (a.z + a.w)) + ((b.x + b.y) + (b.z + b.w));
;   return rsqrtf(s * (1.f / DM) + EPS);
; }
;   __device__ __forceinline__ void operator()(EPI_ARGS) {
;     int tile = fc0 >> 8;
;     _Pragma("unroll") for (int bj = 0; bj < 2; ++bj) _Pragma("unroll") for (int n = 0; n < 2; ++n) {
;       int t = S_TOK(bj, n); float rs = row_rs(rowss, t); u16* d = act + (long)t * DFF + tile * 128 + wr * 64 + fq * 4;
;       _Pragma("unroll") for (int m = 0; m < 4; ++m) {
;         f32x4 g = acc[0][bj][m][n], u = acc[1][bj][m][n]; float v[4];
;         _Pragma("unroll") for (int j = 0; j < 4; ++j) v[j] = silu_f(g[j] * rs) * (u[j] * rs);
;         *(uint2*)(d + m * 16) = pack4(v[0], v[1], v[2], v[3]);
;       }
;     }
.LBB0_2237:
	s_mov_b32 s0, -1
	s_movk_i32 s16, 0x1600
	v_mbcnt_lo_u32_b32 v32, s0, 0
	v_mbcnt_hi_u32_b32 v32, s0, v32
	v_or_b32_e32 v32, s97, v32
	s_ashr_i32 s0, s20, 1
	v_lshrrev_b32_e32 v144, 1, v32
	v_and_b32_e32 v130, 15, v32
	v_and_b32_e32 v131, 0x60, v144
	v_add3_u32 v130, v130, s19, v131
	v_ashrrev_i32_e32 v131, 31, v130
	v_lshlrev_b64 v[132:133], 5, v[130:131]
	v_lshl_add_u64 v[136:137], s[6:7], 0, v[132:133]
	v_add_u32_e32 v186, 0x80, v130
	v_ashrrev_i32_e32 v187, 31, v186
	v_lshlrev_b64 v[186:187], 5, v[186:187]
	v_lshl_add_u64 v[186:187], s[6:7], 0, v[186:187]
	global_load_dwordx4 v[190:193], v[186:187], off offset:-4080
	global_load_dwordx4 v[194:197], v[186:187], off offset:-4096
	global_load_dwordx4 v[198:201], v[186:187], off offset:-3568
	global_load_dwordx4 v[202:205], v[186:187], off offset:-3584
	global_load_dwordx4 v[206:209], v[186:187], off offset:16
	global_load_dwordx4 v[210:213], v[186:187], off
	global_load_dwordx4 v[214:217], v[186:187], off offset:528
	global_load_dwordx4 v[218:221], v[186:187], off offset:512
	s_waitcnt vmcnt(6)
	v_mov_b32_e32 v132, v190
	v_mov_b32_e32 v133, v191
	v_mov_b32_e32 v134, v192
	v_mov_b32_e32 v135, v193
	s_nop 0
	v_mov_b32_e32 v136, v194
	v_mov_b32_e32 v137, v195
	v_mov_b32_e32 v138, v196
	v_mov_b32_e32 v139, v197
	v_ashrrev_i32_e32 v32, 2, v32
	v_and_b32_e32 v140, 0xffffffc0, v32
	s_ashr_i32 s1, s0, 31
	v_ashrrev_i32_e32 v141, 31, v140
	s_lshl_b64 s[0:1], s[0:1], 1
	s_nop 0
	v_mov_b32_e32 v143, v132
	s_nop 0
	v_mov_b32_e32 v142, v136
	v_mov_b32_e32 v132, v137
	v_mov_b32_e32 v136, v138
	v_mov_b32_e32 v137, v134
	v_mov_b32_e32 v134, v139
	v_pk_add_f32 v[132:133], v[142:143], v[132:133]
	v_pk_add_f32 v[134:135], v[136:137], v[134:135]
	s_nop 0
	v_pk_add_f32 v[132:133], v[132:133], v[134:135]
	s_nop 0
	v_add_f32_e32 v32, v132, v133
	v_fmamk_f32 v32, v32, 0x3a800000, v162
	v_cmp_gt_f32_e32 vcc, s75, v32
	v_mul_f32_e32 v131, 0x4b800000, v32
	v_mov_b64_e32 v[132:133], s[12:13]
	v_cndmask_b32_e32 v32, v32, v131, vcc
	v_rsq_f32_e32 v32, v32
	v_mad_i64_i32 v[134:135], s[10:11], v130, s16, v[132:133]
	v_lshl_add_u64 v[138:139], v[134:135], 0, s[0:1]
	v_mul_f32_e32 v131, 0x45800000, v32
	v_cndmask_b32_e32 v136, v32, v131, vcc
	v_pk_mul_f32 v[122:123], v[122:123], v[136:137] op_sel_hi:[1,0]
	v_lshlrev_b64 v[134:135], 1, v[140:141]
	v_mul_f32_e32 v131, 0xbfb8aa3b, v122
	v_exp_f32_e32 v131, v131
	v_pk_mul_f32 v[126:127], v[126:127], v[136:137] op_sel_hi:[1,0]
	v_pk_mul_f32 v[124:125], v[124:125], v[136:137] op_sel_hi:[1,0]
	v_lshl_add_u64 v[138:139], v[138:139], 0, v[134:135]
	v_add_f32_e32 v131, 1.0, v131
	v_rcp_f32_e32 v140, v131
	v_mul_f32_e32 v131, 0xbfb8aa3b, v123
	v_exp_f32_e32 v131, v131
	v_and_b32_e32 v32, 24, v144
	v_lshl_add_u64 v[138:139], v[138:139], 0, v[32:33]
	v_pk_mul_f32 v[114:115], v[114:115], v[136:137] op_sel_hi:[1,0]
	v_add_f32_e32 v131, 1.0, v131
	v_rcp_f32_e32 v141, v131
	v_pk_mul_f32 v[118:119], v[118:119], v[136:137] op_sel_hi:[1,0]
	v_pk_mul_f32 v[116:117], v[116:117], v[136:137] op_sel_hi:[1,0]
	v_pk_mul_f32 v[110:111], v[110:111], v[136:137] op_sel_hi:[1,0]
	v_pk_mul_f32 v[122:123], v[122:123], v[140:141]
	v_pk_mul_f32 v[106:107], v[106:107], v[136:137] op_sel_hi:[1,0]
	v_pk_mul_f32 v[122:123], v[126:127], v[122:123]
	v_mul_f32_e32 v126, 0xbfb8aa3b, v124
	v_mul_f32_e32 v127, 0xbfb8aa3b, v125
	v_exp_f32_e32 v126, v126
	v_exp_f32_e32 v127, v127
	v_cvt_pk_bf16_f32 v122, v122, v123
	v_pk_mul_f32 v[108:109], v[108:109], v[136:137] op_sel_hi:[1,0]
	v_add_f32_e32 v126, 1.0, v126
	v_add_f32_e32 v127, 1.0, v127
	v_rcp_f32_e32 v126, v126
	v_rcp_f32_e32 v127, v127
	v_pk_mul_f32 v[98:99], v[98:99], v[136:137] op_sel_hi:[1,0]
	v_pk_mul_f32 v[102:103], v[102:103], v[136:137] op_sel_hi:[1,0]
	v_pk_mul_f32 v[100:101], v[100:101], v[136:137] op_sel_hi:[1,0]
	v_pk_mul_f32 v[124:125], v[124:125], v[126:127]
	v_pk_mul_f32 v[126:127], v[128:129], v[136:137] op_sel_hi:[1,0]
	s_nop 0
	v_pk_mul_f32 v[124:125], v[126:127], v[124:125]
	s_nop 0
	v_cvt_pk_bf16_f32 v123, v124, v125
	global_store_dwordx2 v[138:139], v[122:123], off
	v_mul_f32_e32 v122, 0xbfb8aa3b, v114
	v_mul_f32_e32 v123, 0xbfb8aa3b, v115
	v_exp_f32_e32 v122, v122
	v_exp_f32_e32 v123, v123
	v_add_f32_e32 v122, 1.0, v122
	v_add_f32_e32 v123, 1.0, v123
	v_rcp_f32_e32 v122, v122
	v_rcp_f32_e32 v123, v123
	s_nop 0
	v_pk_mul_f32 v[114:115], v[114:115], v[122:123]
	s_nop 0
	v_pk_mul_f32 v[114:115], v[118:119], v[114:115]
	v_mul_f32_e32 v118, 0xbfb8aa3b, v116
	v_mul_f32_e32 v119, 0xbfb8aa3b, v117
	v_exp_f32_e32 v118, v118
	v_exp_f32_e32 v119, v119
	v_cvt_pk_bf16_f32 v114, v114, v115
	v_add_f32_e32 v118, 1.0, v118
	v_add_f32_e32 v119, 1.0, v119
	v_rcp_f32_e32 v118, v118
	v_rcp_f32_e32 v119, v119
	s_nop 0
	v_pk_mul_f32 v[116:117], v[116:117], v[118:119]
	v_pk_mul_f32 v[118:119], v[120:121], v[136:137] op_sel_hi:[1,0]
	s_nop 0
	v_pk_mul_f32 v[116:117], v[118:119], v[116:117]
	s_nop 0
	v_cvt_pk_bf16_f32 v115, v116, v117
	global_store_dwordx2 v[138:139], v[114:115], off offset:32
	v_mul_f32_e32 v114, 0xbfb8aa3b, v110
	v_mul_f32_e32 v115, 0xbfb8aa3b, v111
	v_exp_f32_e32 v114, v114
	v_exp_f32_e32 v115, v115
	v_add_f32_e32 v114, 1.0, v114
	v_add_f32_e32 v115, 1.0, v115
	v_rcp_f32_e32 v114, v114
	v_rcp_f32_e32 v115, v115
	s_nop 0
	v_pk_mul_f32 v[110:111], v[110:111], v[114:115]
	s_nop 0
	v_pk_mul_f32 v[106:107], v[106:107], v[110:111]
	v_pk_mul_f32 v[110:111], v[112:113], v[136:137] op_sel_hi:[1,0]
	v_cvt_pk_bf16_f32 v106, v106, v107
	v_mul_f32_e32 v112, 0xbfb8aa3b, v110
	v_mul_f32_e32 v113, 0xbfb8aa3b, v111
	v_exp_f32_e32 v112, v112
	v_exp_f32_e32 v113, v113
	v_add_f32_e32 v112, 1.0, v112
	v_add_f32_e32 v113, 1.0, v113
	v_rcp_f32_e32 v112, v112
	v_rcp_f32_e32 v113, v113
	s_nop 0
	v_pk_mul_f32 v[110:111], v[110:111], v[112:113]
	s_nop 0
	v_pk_mul_f32 v[108:109], v[108:109], v[110:111]
	s_nop 0
	v_cvt_pk_bf16_f32 v107, v108, v109
	global_store_dwordx2 v[138:139], v[106:107], off offset:64
	v_mul_f32_e32 v106, 0xbfb8aa3b, v98
	v_mul_f32_e32 v107, 0xbfb8aa3b, v99
	v_exp_f32_e32 v106, v106
	v_exp_f32_e32 v107, v107
	v_add_f32_e32 v106, 1.0, v106
	v_add_f32_e32 v107, 1.0, v107
	v_rcp_f32_e32 v106, v106
	v_rcp_f32_e32 v107, v107
	s_nop 0
	v_pk_mul_f32 v[98:99], v[98:99], v[106:107]
	s_nop 0
	v_pk_mul_f32 v[98:99], v[102:103], v[98:99]
	v_mul_f32_e32 v102, 0xbfb8aa3b, v100
	v_mul_f32_e32 v103, 0xbfb8aa3b, v101
	v_exp_f32_e32 v102, v102
	v_exp_f32_e32 v103, v103
	v_add_u32_e32 v106, 16, v130
	v_cvt_pk_bf16_f32 v98, v98, v99
	v_add_f32_e32 v102, 1.0, v102
	v_add_f32_e32 v103, 1.0, v103
	v_rcp_f32_e32 v102, v102
	v_rcp_f32_e32 v103, v103
	v_ashrrev_i32_e32 v107, 31, v106
	v_pk_mul_f32 v[100:101], v[100:101], v[102:103]
	v_pk_mul_f32 v[102:103], v[104:105], v[136:137] op_sel_hi:[1,0]
	s_nop 0
	v_pk_mul_f32 v[100:101], v[102:103], v[100:101]
	s_nop 0
	v_cvt_pk_bf16_f32 v99, v100, v101
	global_store_dwordx2 v[138:139], v[98:99], off offset:96
	v_lshlrev_b64 v[98:99], 5, v[106:107]
	v_lshl_add_u64 v[102:103], s[6:7], 0, v[98:99]
	s_waitcnt vmcnt(8)
; __device__ __forceinline__ float silu_f(float x) { return x * sigmoid_f(x); }
; __device__ __forceinline__ uint2 pack4(float a, float b, float c, float d) { uint2 r; r.x = pk2(a, b); r.y = pk2(c, d); return r; }
; __device__ __forceinline__ float row_rs(const float* part, int row) {
;   const float4* q = (const float4*)(part + (long)row * 8);
;   float4 a = q[0], b = q[1];
;   float s = ((a.x + a.y) + (a.z + a.w)) + ((b.x + b.y) + (b.z + b.w));
;   return rsqrtf(s * (1.f / DM) + EPS);
; }
;   __device__ __forceinline__ void operator()(EPI_ARGS) {
;     int tile = fc0 >> 8;
;     _Pragma("unroll") for (int bj = 0; bj < 2; ++bj) _Pragma("unroll") for (int n = 0; n < 2; ++n) {
;       int t = S_TOK(bj, n); float rs = row_rs(rowss, t); u16* d = act + (long)t * DFF + tile * 128 + wr * 64 + fq * 4;
;       _Pragma("unroll") for (int m = 0; m < 4; ++m) {
;         f32x4 g = acc[0][bj][m][n], u = acc[1][bj][m][n]; float v[4];
;         _Pragma("unroll") for (int j = 0; j < 4; ++j) v[j] = silu_f(g[j] * rs) * (u[j] * rs);
;         *(uint2*)(d + m * 16) = pack4(v[0], v[1], v[2], v[3]);
;       }
;     }
	v_mov_b32_e32 v98, v198
	v_mov_b32_e32 v99, v199
	v_mov_b32_e32 v100, v200
	v_mov_b32_e32 v101, v201
	s_nop 0
	v_mov_b32_e32 v102, v202
	v_mov_b32_e32 v103, v203
	v_mov_b32_e32 v104, v204
	v_mov_b32_e32 v105, v205
	s_nop 0
	v_mov_b32_e32 v109, v98
	s_nop 0
	v_mov_b32_e32 v108, v102
	v_mov_b32_e32 v98, v103
	v_mov_b32_e32 v102, v104
	v_mov_b32_e32 v103, v100
	v_mov_b32_e32 v100, v105
	v_pk_add_f32 v[98:99], v[108:109], v[98:99]
	v_pk_add_f32 v[100:101], v[102:103], v[100:101]
	s_nop 0
	v_pk_add_f32 v[98:99], v[98:99], v[100:101]
	v_mad_i64_i32 v[100:101], s[10:11], v106, s16, v[132:133]
	v_add_f32_e32 v98, v98, v99
	v_fmamk_f32 v98, v98, 0x3a800000, v162
	v_cmp_gt_f32_e32 vcc, s75, v98
	v_mul_f32_e32 v99, 0x4b800000, v98
	v_lshl_add_u64 v[100:101], v[100:101], 0, s[0:1]
	v_cndmask_b32_e32 v98, v98, v99, vcc
	v_rsq_f32_e32 v98, v98
	v_lshl_add_u64 v[100:101], v[100:101], 0, v[134:135]
	v_lshl_add_u64 v[100:101], v[100:101], 0, v[32:33]
	v_mul_f32_e32 v99, 0x45800000, v98
	v_cndmask_b32_e32 v98, v98, v99, vcc
	v_pk_mul_f32 v[90:91], v[90:91], v[98:99] op_sel_hi:[1,0]
	s_nop 0
	v_mul_f32_e32 v99, 0xbfb8aa3b, v90
	v_exp_f32_e32 v99, v99
	s_nop 0
	v_add_f32_e32 v99, 1.0, v99
	v_rcp_f32_e32 v102, v99
	v_mul_f32_e32 v99, 0xbfb8aa3b, v91
	v_exp_f32_e32 v99, v99
	s_nop 0
	v_add_f32_e32 v99, 1.0, v99
	v_rcp_f32_e32 v103, v99
	v_pk_mul_f32 v[94:95], v[94:95], v[98:99] op_sel_hi:[1,0]
	v_pk_mul_f32 v[92:93], v[92:93], v[98:99] op_sel_hi:[1,0]
	v_pk_mul_f32 v[86:87], v[86:87], v[98:99] op_sel_hi:[1,0]
	v_pk_mul_f32 v[90:91], v[90:91], v[102:103]
	v_pk_mul_f32 v[82:83], v[82:83], v[98:99] op_sel_hi:[1,0]
	v_pk_mul_f32 v[90:91], v[94:95], v[90:91]
	v_mul_f32_e32 v94, 0xbfb8aa3b, v92
	v_mul_f32_e32 v95, 0xbfb8aa3b, v93
	v_exp_f32_e32 v94, v94
	v_exp_f32_e32 v95, v95
	v_cvt_pk_bf16_f32 v90, v90, v91
	v_pk_mul_f32 v[84:85], v[84:85], v[98:99] op_sel_hi:[1,0]
	v_add_f32_e32 v94, 1.0, v94
	v_add_f32_e32 v95, 1.0, v95
	v_rcp_f32_e32 v94, v94
	v_rcp_f32_e32 v95, v95
	v_pk_mul_f32 v[74:75], v[74:75], v[98:99] op_sel_hi:[1,0]
	v_pk_mul_f32 v[78:79], v[78:79], v[98:99] op_sel_hi:[1,0]
	v_pk_mul_f32 v[76:77], v[76:77], v[98:99] op_sel_hi:[1,0]
	v_pk_mul_f32 v[92:93], v[92:93], v[94:95]
	v_pk_mul_f32 v[94:95], v[96:97], v[98:99] op_sel_hi:[1,0]
	v_pk_mul_f32 v[66:67], v[66:67], v[98:99] op_sel_hi:[1,0]
	v_pk_mul_f32 v[92:93], v[94:95], v[92:93]
	v_pk_mul_f32 v[70:71], v[70:71], v[98:99] op_sel_hi:[1,0]
	v_cvt_pk_bf16_f32 v91, v92, v93
	global_store_dwordx2 v[100:101], v[90:91], off
	v_mul_f32_e32 v90, 0xbfb8aa3b, v86
	v_mul_f32_e32 v91, 0xbfb8aa3b, v87
	v_exp_f32_e32 v90, v90
	v_exp_f32_e32 v91, v91
	v_pk_mul_f32 v[68:69], v[68:69], v[98:99] op_sel_hi:[1,0]
	v_add_f32_e32 v90, 1.0, v90
	v_add_f32_e32 v91, 1.0, v91
	v_rcp_f32_e32 v90, v90
	v_rcp_f32_e32 v91, v91
	s_nop 0
	v_pk_mul_f32 v[86:87], v[86:87], v[90:91]
	s_nop 0
	v_pk_mul_f32 v[82:83], v[82:83], v[86:87]
	v_pk_mul_f32 v[86:87], v[88:89], v[98:99] op_sel_hi:[1,0]
	v_cvt_pk_bf16_f32 v82, v82, v83
	v_mul_f32_e32 v88, 0xbfb8aa3b, v86
	v_mul_f32_e32 v89, 0xbfb8aa3b, v87
	v_exp_f32_e32 v88, v88
	v_exp_f32_e32 v89, v89
	v_add_f32_e32 v88, 1.0, v88
	v_add_f32_e32 v89, 1.0, v89
	v_rcp_f32_e32 v88, v88
	v_rcp_f32_e32 v89, v89
	s_nop 0
	v_pk_mul_f32 v[86:87], v[86:87], v[88:89]
	s_nop 0
	v_pk_mul_f32 v[84:85], v[84:85], v[86:87]
	s_nop 0
	v_cvt_pk_bf16_f32 v83, v84, v85
	global_store_dwordx2 v[100:101], v[82:83], off offset:32
	v_mul_f32_e32 v82, 0xbfb8aa3b, v74
	v_mul_f32_e32 v83, 0xbfb8aa3b, v75
	v_exp_f32_e32 v82, v82
	v_exp_f32_e32 v83, v83
	v_add_f32_e32 v82, 1.0, v82
	v_add_f32_e32 v83, 1.0, v83
	v_rcp_f32_e32 v82, v82
	v_rcp_f32_e32 v83, v83
	s_nop 0
	v_pk_mul_f32 v[74:75], v[74:75], v[82:83]
	s_nop 0
	v_pk_mul_f32 v[74:75], v[78:79], v[74:75]
	v_mul_f32_e32 v78, 0xbfb8aa3b, v76
	v_mul_f32_e32 v79, 0xbfb8aa3b, v77
	v_exp_f32_e32 v78, v78
	v_exp_f32_e32 v79, v79
	v_cvt_pk_bf16_f32 v74, v74, v75
	v_add_f32_e32 v78, 1.0, v78
	v_add_f32_e32 v79, 1.0, v79
	v_rcp_f32_e32 v78, v78
	v_rcp_f32_e32 v79, v79
	s_nop 0
	v_pk_mul_f32 v[76:77], v[76:77], v[78:79]
	v_pk_mul_f32 v[78:79], v[80:81], v[98:99] op_sel_hi:[1,0]
	s_nop 0
	v_pk_mul_f32 v[76:77], v[78:79], v[76:77]
	s_nop 0
	v_cvt_pk_bf16_f32 v75, v76, v77
	global_store_dwordx2 v[100:101], v[74:75], off offset:64
	v_mul_f32_e32 v74, 0xbfb8aa3b, v66
	v_mul_f32_e32 v75, 0xbfb8aa3b, v67
	v_exp_f32_e32 v74, v74
	v_exp_f32_e32 v75, v75
	v_add_f32_e32 v74, 1.0, v74
	v_add_f32_e32 v75, 1.0, v75
	v_rcp_f32_e32 v74, v74
	v_rcp_f32_e32 v75, v75
	s_nop 0
	v_pk_mul_f32 v[66:67], v[66:67], v[74:75]
	s_nop 0
	v_pk_mul_f32 v[66:67], v[70:71], v[66:67]
	v_mul_f32_e32 v70, 0xbfb8aa3b, v68
	v_mul_f32_e32 v71, 0xbfb8aa3b, v69
	v_exp_f32_e32 v70, v70
	v_exp_f32_e32 v71, v71
	v_add_u32_e32 v74, 0x80, v130
	v_cvt_pk_bf16_f32 v66, v66, v67
	v_add_f32_e32 v70, 1.0, v70
	v_add_f32_e32 v71, 1.0, v71
	v_rcp_f32_e32 v70, v70
	v_rcp_f32_e32 v71, v71
	v_ashrrev_i32_e32 v75, 31, v74
	v_pk_mul_f32 v[68:69], v[68:69], v[70:71]
	v_pk_mul_f32 v[70:71], v[72:73], v[98:99] op_sel_hi:[1,0]
	s_nop 0
	v_pk_mul_f32 v[68:69], v[70:71], v[68:69]
	s_nop 0
	v_cvt_pk_bf16_f32 v67, v68, v69
	global_store_dwordx2 v[100:101], v[66:67], off offset:96
	v_lshlrev_b64 v[66:67], 5, v[74:75]
	v_lshl_add_u64 v[70:71], s[6:7], 0, v[66:67]
	s_waitcnt vmcnt(10)
; __device__ __forceinline__ float silu_f(float x) { return x * sigmoid_f(x); }
; __device__ __forceinline__ uint2 pack4(float a, float b, float c, float d) { uint2 r; r.x = pk2(a, b); r.y = pk2(c, d); return r; }
; __device__ __forceinline__ float row_rs(const float* part, int row) {
;   const float4* q = (const float4*)(part + (long)row * 8);
;   float4 a = q[0], b = q[1];
;   float s = ((a.x + a.y) + (a.z + a.w)) + ((b.x + b.y) + (b.z + b.w));
;   return rsqrtf(s * (1.f / DM) + EPS);
; }
;   __device__ __forceinline__ void operator()(EPI_ARGS) {
;     int tile = fc0 >> 8;
;     _Pragma("unroll") for (int bj = 0; bj < 2; ++bj) _Pragma("unroll") for (int n = 0; n < 2; ++n) {
;       int t = S_TOK(bj, n); float rs = row_rs(rowss, t); u16* d = act + (long)t * DFF + tile * 128 + wr * 64 + fq * 4;
;       _Pragma("unroll") for (int m = 0; m < 4; ++m) {
;         f32x4 g = acc[0][bj][m][n], u = acc[1][bj][m][n]; float v[4];
;         _Pragma("unroll") for (int j = 0; j < 4; ++j) v[j] = silu_f(g[j] * rs) * (u[j] * rs);
;         *(uint2*)(d + m * 16) = pack4(v[0], v[1], v[2], v[3]);
;       }
;     }
	v_mov_b32_e32 v66, v206
	v_mov_b32_e32 v67, v207
	v_mov_b32_e32 v68, v208
	v_mov_b32_e32 v69, v209
	s_nop 0
	v_mov_b32_e32 v70, v210
	v_mov_b32_e32 v71, v211
	v_mov_b32_e32 v72, v212
	v_mov_b32_e32 v73, v213
	s_nop 0
	v_mov_b32_e32 v77, v66
	s_nop 0
	v_mov_b32_e32 v76, v70
	v_mov_b32_e32 v66, v71
	v_mov_b32_e32 v70, v72
	v_mov_b32_e32 v71, v68
	v_mov_b32_e32 v68, v73
	v_pk_add_f32 v[66:67], v[76:77], v[66:67]
	v_pk_add_f32 v[68:69], v[70:71], v[68:69]
	s_nop 0
	v_pk_add_f32 v[66:67], v[66:67], v[68:69]
	v_mad_i64_i32 v[68:69], s[10:11], v74, s16, v[132:133]
	v_add_f32_e32 v66, v66, v67
	v_fmamk_f32 v66, v66, 0x3a800000, v162
	v_cmp_gt_f32_e32 vcc, s75, v66
	v_mul_f32_e32 v67, 0x4b800000, v66
	v_lshl_add_u64 v[68:69], v[68:69], 0, s[0:1]
	v_cndmask_b32_e32 v66, v66, v67, vcc
	v_rsq_f32_e32 v66, v66
	v_lshl_add_u64 v[68:69], v[68:69], 0, v[134:135]
	v_lshl_add_u64 v[68:69], v[68:69], 0, v[32:33]
	v_mul_f32_e32 v67, 0x45800000, v66
	v_cndmask_b32_e32 v66, v66, v67, vcc
	v_pk_mul_f32 v[62:63], v[62:63], v[66:67] op_sel_hi:[1,0]
	s_nop 0
	v_mul_f32_e32 v67, 0xbfb8aa3b, v62
	v_exp_f32_e32 v67, v67
	s_nop 0
	v_add_f32_e32 v67, 1.0, v67
	v_rcp_f32_e32 v70, v67
	v_mul_f32_e32 v67, 0xbfb8aa3b, v63
	v_exp_f32_e32 v67, v67
	s_nop 0
	v_add_f32_e32 v67, 1.0, v67
	v_rcp_f32_e32 v71, v67
	v_pk_mul_f32 v[58:59], v[58:59], v[66:67] op_sel_hi:[1,0]
	v_pk_mul_f32 v[60:61], v[60:61], v[66:67] op_sel_hi:[1,0]
	v_pk_mul_f32 v[50:51], v[50:51], v[66:67] op_sel_hi:[1,0]
	v_pk_mul_f32 v[62:63], v[62:63], v[70:71]
	v_pk_mul_f32 v[54:55], v[54:55], v[66:67] op_sel_hi:[1,0]
	v_pk_mul_f32 v[58:59], v[58:59], v[62:63]
	v_pk_mul_f32 v[62:63], v[64:65], v[66:67] op_sel_hi:[1,0]
	v_cvt_pk_bf16_f32 v58, v58, v59
	v_mul_f32_e32 v64, 0xbfb8aa3b, v62
	v_mul_f32_e32 v65, 0xbfb8aa3b, v63
	v_exp_f32_e32 v64, v64
	v_exp_f32_e32 v65, v65
	v_pk_mul_f32 v[52:53], v[52:53], v[66:67] op_sel_hi:[1,0]
	v_pk_mul_f32 v[42:43], v[42:43], v[66:67] op_sel_hi:[1,0]
	v_add_f32_e32 v64, 1.0, v64
	v_add_f32_e32 v65, 1.0, v65
	v_rcp_f32_e32 v64, v64
	v_rcp_f32_e32 v65, v65
	v_pk_mul_f32 v[46:47], v[46:47], v[66:67] op_sel_hi:[1,0]
	v_pk_mul_f32 v[44:45], v[44:45], v[66:67] op_sel_hi:[1,0]
	v_pk_mul_f32 v[34:35], v[34:35], v[66:67] op_sel_hi:[1,0]
	v_pk_mul_f32 v[62:63], v[62:63], v[64:65]
	v_pk_mul_f32 v[38:39], v[38:39], v[66:67] op_sel_hi:[1,0]
	v_pk_mul_f32 v[60:61], v[60:61], v[62:63]
	v_pk_mul_f32 v[36:37], v[36:37], v[66:67] op_sel_hi:[1,0]
	v_cvt_pk_bf16_f32 v59, v60, v61
	global_store_dwordx2 v[68:69], v[58:59], off
	v_mul_f32_e32 v58, 0xbfb8aa3b, v50
	v_mul_f32_e32 v59, 0xbfb8aa3b, v51
	v_exp_f32_e32 v58, v58
	v_exp_f32_e32 v59, v59
	v_add_f32_e32 v58, 1.0, v58
	v_add_f32_e32 v59, 1.0, v59
	v_rcp_f32_e32 v58, v58
	v_rcp_f32_e32 v59, v59
	s_nop 0
	v_pk_mul_f32 v[50:51], v[50:51], v[58:59]
	s_nop 0
	v_pk_mul_f32 v[50:51], v[54:55], v[50:51]
	v_mul_f32_e32 v54, 0xbfb8aa3b, v52
	v_mul_f32_e32 v55, 0xbfb8aa3b, v53
	v_exp_f32_e32 v54, v54
	v_exp_f32_e32 v55, v55
	v_cvt_pk_bf16_f32 v50, v50, v51
	v_add_f32_e32 v54, 1.0, v54
	v_add_f32_e32 v55, 1.0, v55
	v_rcp_f32_e32 v54, v54
	v_rcp_f32_e32 v55, v55
	s_nop 0
	v_pk_mul_f32 v[52:53], v[52:53], v[54:55]
	v_pk_mul_f32 v[54:55], v[56:57], v[66:67] op_sel_hi:[1,0]
	s_nop 0
	v_pk_mul_f32 v[52:53], v[54:55], v[52:53]
	s_nop 0
	v_cvt_pk_bf16_f32 v51, v52, v53
	global_store_dwordx2 v[68:69], v[50:51], off offset:32
	v_mul_f32_e32 v50, 0xbfb8aa3b, v42
	v_mul_f32_e32 v51, 0xbfb8aa3b, v43
	v_exp_f32_e32 v50, v50
	v_exp_f32_e32 v51, v51
	v_add_f32_e32 v50, 1.0, v50
	v_add_f32_e32 v51, 1.0, v51
	v_rcp_f32_e32 v50, v50
	v_rcp_f32_e32 v51, v51
	s_nop 0
	v_pk_mul_f32 v[42:43], v[42:43], v[50:51]
	s_nop 0
	v_pk_mul_f32 v[42:43], v[46:47], v[42:43]
	v_mul_f32_e32 v46, 0xbfb8aa3b, v44
	v_mul_f32_e32 v47, 0xbfb8aa3b, v45
	v_exp_f32_e32 v46, v46
	v_exp_f32_e32 v47, v47
	v_cvt_pk_bf16_f32 v42, v42, v43
	v_add_f32_e32 v46, 1.0, v46
	v_add_f32_e32 v47, 1.0, v47
	v_rcp_f32_e32 v46, v46
	v_rcp_f32_e32 v47, v47
	s_nop 0
	v_pk_mul_f32 v[44:45], v[44:45], v[46:47]
	v_pk_mul_f32 v[46:47], v[48:49], v[66:67] op_sel_hi:[1,0]
	s_nop 0
	v_pk_mul_f32 v[44:45], v[46:47], v[44:45]
	s_nop 0
	v_cvt_pk_bf16_f32 v43, v44, v45
	global_store_dwordx2 v[68:69], v[42:43], off offset:64
	v_mul_f32_e32 v42, 0xbfb8aa3b, v34
	v_mul_f32_e32 v43, 0xbfb8aa3b, v35
	v_exp_f32_e32 v42, v42
	v_exp_f32_e32 v43, v43
	v_add_f32_e32 v42, 1.0, v42
	v_add_f32_e32 v43, 1.0, v43
	v_rcp_f32_e32 v42, v42
	v_rcp_f32_e32 v43, v43
	s_nop 0
	v_pk_mul_f32 v[34:35], v[34:35], v[42:43]
	s_nop 0
	v_pk_mul_f32 v[34:35], v[38:39], v[34:35]
	v_mul_f32_e32 v38, 0xbfb8aa3b, v36
	v_mul_f32_e32 v39, 0xbfb8aa3b, v37
	v_exp_f32_e32 v38, v38
	v_exp_f32_e32 v39, v39
	v_add_u32_e32 v42, 0x90, v130
	v_cvt_pk_bf16_f32 v34, v34, v35
	v_add_f32_e32 v38, 1.0, v38
	v_add_f32_e32 v39, 1.0, v39
	v_rcp_f32_e32 v38, v38
	v_rcp_f32_e32 v39, v39
	v_ashrrev_i32_e32 v43, 31, v42
	v_pk_mul_f32 v[36:37], v[36:37], v[38:39]
	v_pk_mul_f32 v[38:39], v[40:41], v[66:67] op_sel_hi:[1,0]
	s_nop 0
	v_pk_mul_f32 v[36:37], v[38:39], v[36:37]
	s_nop 0
	v_cvt_pk_bf16_f32 v35, v36, v37
	global_store_dwordx2 v[68:69], v[34:35], off offset:96
	v_lshlrev_b64 v[34:35], 5, v[42:43]
	v_lshl_add_u64 v[38:39], s[6:7], 0, v[34:35]
	s_waitcnt vmcnt(12)
; __device__ __forceinline__ float silu_f(float x) { return x * sigmoid_f(x); }
; __device__ __forceinline__ uint2 pack4(float a, float b, float c, float d) { uint2 r; r.x = pk2(a, b); r.y = pk2(c, d); return r; }
; __device__ __forceinline__ float row_rs(const float* part, int row) {
;   const float4* q = (const float4*)(part + (long)row * 8);
;   float4 a = q[0], b = q[1];
;   float s = ((a.x + a.y) + (a.z + a.w)) + ((b.x + b.y) + (b.z + b.w));
;   return rsqrtf(s * (1.f / DM) + EPS);
; }
;   __device__ __forceinline__ void operator()(EPI_ARGS) {
;     int tile = fc0 >> 8;
;     _Pragma("unroll") for (int bj = 0; bj < 2; ++bj) _Pragma("unroll") for (int n = 0; n < 2; ++n) {
;       int t = S_TOK(bj, n); float rs = row_rs(rowss, t); u16* d = act + (long)t * DFF + tile * 128 + wr * 64 + fq * 4;
;       _Pragma("unroll") for (int m = 0; m < 4; ++m) {
;         f32x4 g = acc[0][bj][m][n], u = acc[1][bj][m][n]; float v[4];
;         _Pragma("unroll") for (int j = 0; j < 4; ++j) v[j] = silu_f(g[j] * rs) * (u[j] * rs);
;         *(uint2*)(d + m * 16) = pack4(v[0], v[1], v[2], v[3]);
;       }
;     }
	v_mov_b32_e32 v34, v214
	v_mov_b32_e32 v35, v215
	v_mov_b32_e32 v36, v216
	v_mov_b32_e32 v37, v217
	s_nop 0
	v_mov_b32_e32 v38, v218
	v_mov_b32_e32 v39, v219
	v_mov_b32_e32 v40, v220
	v_mov_b32_e32 v41, v221
	s_nop 0
	v_mov_b32_e32 v45, v34
	s_nop 0
	v_mov_b32_e32 v44, v38
	v_mov_b32_e32 v34, v39
	v_mov_b32_e32 v38, v40
	v_mov_b32_e32 v39, v36
	v_mov_b32_e32 v36, v41
	v_pk_add_f32 v[34:35], v[44:45], v[34:35]
	v_pk_add_f32 v[36:37], v[38:39], v[36:37]
	s_nop 0
	v_pk_add_f32 v[34:35], v[34:35], v[36:37]
	s_nop 0
	v_add_f32_e32 v34, v34, v35
	v_fmamk_f32 v34, v34, 0x3a800000, v162
	v_cmp_gt_f32_e32 vcc, s75, v34
	v_mul_f32_e32 v35, 0x4b800000, v34
	s_nop 0
	v_cndmask_b32_e32 v34, v34, v35, vcc
	v_rsq_f32_e32 v34, v34
	s_nop 0
	v_mul_f32_e32 v35, 0x45800000, v34
	v_cndmask_b32_e32 v36, v34, v35, vcc
	v_mad_i64_i32 v[34:35], s[10:11], v42, s16, v[132:133]
	v_lshl_add_u64 v[34:35], v[34:35], 0, s[0:1]
	v_lshl_add_u64 v[34:35], v[34:35], 0, v[134:135]
	v_pk_mul_f32 v[24:25], v[24:25], v[36:37] op_sel_hi:[1,0]
	v_lshl_add_u64 v[34:35], v[34:35], 0, v[32:33]
	v_mul_f32_e32 v32, 0xbfb8aa3b, v24
	v_exp_f32_e32 v32, v32
	v_pk_mul_f32 v[28:29], v[28:29], v[36:37] op_sel_hi:[1,0]
	v_pk_mul_f32 v[26:27], v[26:27], v[36:37] op_sel_hi:[1,0]
	v_pk_mul_f32 v[16:17], v[16:17], v[36:37] op_sel_hi:[1,0]
	v_add_f32_e32 v32, 1.0, v32
	v_rcp_f32_e32 v38, v32
	v_mul_f32_e32 v32, 0xbfb8aa3b, v25
	v_exp_f32_e32 v32, v32
	v_pk_mul_f32 v[20:21], v[20:21], v[36:37] op_sel_hi:[1,0]
	v_pk_mul_f32 v[18:19], v[18:19], v[36:37] op_sel_hi:[1,0]
	v_pk_mul_f32 v[8:9], v[8:9], v[36:37] op_sel_hi:[1,0]
	v_add_f32_e32 v32, 1.0, v32
	v_rcp_f32_e32 v39, v32
	v_pk_mul_f32 v[12:13], v[12:13], v[36:37] op_sel_hi:[1,0]
	v_pk_mul_f32 v[10:11], v[10:11], v[36:37] op_sel_hi:[1,0]
	v_pk_mul_f32 v[0:1], v[0:1], v[36:37] op_sel_hi:[1,0]
	v_pk_mul_f32 v[24:25], v[24:25], v[38:39]
	v_pk_mul_f32 v[4:5], v[4:5], v[36:37] op_sel_hi:[1,0]
	v_pk_mul_f32 v[24:25], v[28:29], v[24:25]
	v_mul_f32_e32 v28, 0xbfb8aa3b, v26
	v_mul_f32_e32 v29, 0xbfb8aa3b, v27
	v_exp_f32_e32 v28, v28
	v_exp_f32_e32 v29, v29
	v_cvt_pk_bf16_f32 v24, v24, v25
	v_pk_mul_f32 v[2:3], v[2:3], v[36:37] op_sel_hi:[1,0]
	v_add_f32_e32 v28, 1.0, v28
	v_add_f32_e32 v29, 1.0, v29
	v_rcp_f32_e32 v28, v28
	v_rcp_f32_e32 v29, v29
	s_mov_b64 s[10:11], -1
	s_andn2_b64 vcc, exec, s[14:15]
	v_pk_mul_f32 v[26:27], v[26:27], v[28:29]
	v_pk_mul_f32 v[28:29], v[30:31], v[36:37] op_sel_hi:[1,0]
	s_nop 0
	v_pk_mul_f32 v[26:27], v[28:29], v[26:27]
	s_nop 0
	v_cvt_pk_bf16_f32 v25, v26, v27
	global_store_dwordx2 v[34:35], v[24:25], off
	v_mul_f32_e32 v24, 0xbfb8aa3b, v16
	v_mul_f32_e32 v25, 0xbfb8aa3b, v17
	v_exp_f32_e32 v24, v24
	v_exp_f32_e32 v25, v25
	v_add_f32_e32 v24, 1.0, v24
	v_add_f32_e32 v25, 1.0, v25
	v_rcp_f32_e32 v24, v24
	v_rcp_f32_e32 v25, v25
	s_nop 0
	v_pk_mul_f32 v[16:17], v[16:17], v[24:25]
	s_nop 0
	v_pk_mul_f32 v[16:17], v[20:21], v[16:17]
	v_mul_f32_e32 v20, 0xbfb8aa3b, v18
	v_mul_f32_e32 v21, 0xbfb8aa3b, v19
	v_exp_f32_e32 v20, v20
	v_exp_f32_e32 v21, v21
	v_cvt_pk_bf16_f32 v16, v16, v17
	v_add_f32_e32 v20, 1.0, v20
	v_add_f32_e32 v21, 1.0, v21
	v_rcp_f32_e32 v20, v20
	v_rcp_f32_e32 v21, v21
	s_nop 0
	v_pk_mul_f32 v[18:19], v[18:19], v[20:21]
	v_pk_mul_f32 v[20:21], v[22:23], v[36:37] op_sel_hi:[1,0]
	s_nop 0
	v_pk_mul_f32 v[18:19], v[20:21], v[18:19]
	s_nop 0
	v_cvt_pk_bf16_f32 v17, v18, v19
	global_store_dwordx2 v[34:35], v[16:17], off offset:32
	v_mul_f32_e32 v16, 0xbfb8aa3b, v8
	v_mul_f32_e32 v17, 0xbfb8aa3b, v9
	v_exp_f32_e32 v16, v16
	v_exp_f32_e32 v17, v17
	v_add_f32_e32 v16, 1.0, v16
	v_add_f32_e32 v17, 1.0, v17
	v_rcp_f32_e32 v16, v16
	v_rcp_f32_e32 v17, v17
	s_nop 0
	v_pk_mul_f32 v[8:9], v[8:9], v[16:17]
	s_nop 0
	v_pk_mul_f32 v[8:9], v[12:13], v[8:9]
	v_mul_f32_e32 v12, 0xbfb8aa3b, v10
	v_mul_f32_e32 v13, 0xbfb8aa3b, v11
	v_exp_f32_e32 v12, v12
	v_exp_f32_e32 v13, v13
	v_cvt_pk_bf16_f32 v8, v8, v9
	v_add_f32_e32 v12, 1.0, v12
	v_add_f32_e32 v13, 1.0, v13
	v_rcp_f32_e32 v12, v12
	v_rcp_f32_e32 v13, v13
	s_nop 0
	v_pk_mul_f32 v[10:11], v[10:11], v[12:13]
	v_pk_mul_f32 v[12:13], v[14:15], v[36:37] op_sel_hi:[1,0]
	s_nop 0
	v_pk_mul_f32 v[10:11], v[12:13], v[10:11]
	s_nop 0
	v_cvt_pk_bf16_f32 v9, v10, v11
	global_store_dwordx2 v[34:35], v[8:9], off offset:64
	v_mul_f32_e32 v8, 0xbfb8aa3b, v0
	v_mul_f32_e32 v9, 0xbfb8aa3b, v1
	v_exp_f32_e32 v8, v8
	v_exp_f32_e32 v9, v9
	v_add_f32_e32 v8, 1.0, v8
	v_add_f32_e32 v9, 1.0, v9
	v_rcp_f32_e32 v8, v8
	v_rcp_f32_e32 v9, v9
	s_nop 0
	v_pk_mul_f32 v[0:1], v[0:1], v[8:9]
	s_nop 0
	v_pk_mul_f32 v[0:1], v[4:5], v[0:1]
	v_mul_f32_e32 v4, 0xbfb8aa3b, v2
	v_mul_f32_e32 v5, 0xbfb8aa3b, v3
	v_exp_f32_e32 v4, v4
	v_exp_f32_e32 v5, v5
	v_cvt_pk_bf16_f32 v0, v0, v1
	v_add_f32_e32 v4, 1.0, v4
	v_add_f32_e32 v5, 1.0, v5
	v_rcp_f32_e32 v4, v4
	v_rcp_f32_e32 v5, v5
	s_nop 0
	v_pk_mul_f32 v[2:3], v[2:3], v[4:5]
	v_pk_mul_f32 v[4:5], v[6:7], v[36:37] op_sel_hi:[1,0]
	s_nop 0
	v_pk_mul_f32 v[2:3], v[4:5], v[2:3]
	s_nop 0
	v_cvt_pk_bf16_f32 v1, v2, v3
	global_store_dwordx2 v[34:35], v[0:1], off offset:96
	s_barrier
	s_cbranch_vccz .LBB0_2261
